# MLA unit body fully hand-scheduled: steady loop plus the diagonal-block tail (per-wave full / last-tile / idle variants), replacing hipcc's tail loop
# speedup vs baseline: 1.0136x; 1.0115x over previous
.LBB0_720:
	s_or_b64 exec, exec, s[10:11]
	s_waitcnt vmcnt(0)
	ds_write_b128 v158, v[126:129] offset:13312
	s_and_saveexec_b64 s[4:5], s[6:7]
	ds_write_b128 v16, v[122:125] offset:13440
	s_or_b64 exec, exec, s[4:5]
	v_lshlrev_b32_e32 v17, 3, v28
	v_lshlrev_b32_e32 v16, 1, v28
	v_and_b32_e32 v17, 24, v17
	v_and_or_b32 v16, v16, 32, v17
	v_lshlrev_b32_e32 v160, 2, v29
	v_lshrrev_b32_e32 v17, 2, v28
	v_and_or_b32 v17, v17, 3, v160
	v_lshl_or_b32 v161, v17, 6, v16
	v_mad_u32_u24 v16, v27, s16, 0
	v_add_u32_e32 v162, v16, v20
	s_waitcnt lgkmcnt(0)
	s_barrier
	ds_read_b128 v[16:19], v162 offset:6656
	ds_read_b128 v[22:25], v162
	ds_read_b128 v[28:31], v162 offset:32
	s_waitcnt lgkmcnt(2)
	v_mfma_f32_32x32x16_bf16 v[62:77], v[16:19], v[0:3], 0
	ds_read_b128 v[16:19], v162 offset:6688
	s_add_i32 s35, s35, 4
	s_mov_b32 s52, 0
	s_cmp_eq_u32 s34, 15
	v_add_u32_e32 v163, v14, v15
	v_add_u32_e32 v150, v21, v26
	s_waitcnt lgkmcnt(2)
	v_mfma_f32_32x32x16_bf16 v[46:61], v[22:25], v[0:3], 0
	s_waitcnt lgkmcnt(1)
	v_mfma_f32_32x32x16_bf16 v[46:61], v[28:31], v[4:7], v[46:61]
	s_waitcnt lgkmcnt(0)
	v_mfma_f32_32x32x16_bf16 v[62:77], v[16:19], v[4:7], v[62:77]
	ds_read_b128 v[16:19], v162 offset:64
	ds_read_b128 v[22:25], v162 offset:6720
	s_waitcnt lgkmcnt(1)
	v_mfma_f32_32x32x16_bf16 v[46:61], v[16:19], v[8:11], v[46:61]
	s_waitcnt lgkmcnt(0)
	v_mfma_f32_32x32x16_bf16 v[62:77], v[22:25], v[8:11], v[62:77]
	ds_read_b128 v[16:19], v162 offset:96
	ds_read_b128 v[22:25], v162 offset:6752
	s_waitcnt lgkmcnt(1)
	v_mfma_f32_32x32x16_bf16 v[46:61], v[16:19], v[110:113], v[46:61]
	s_waitcnt lgkmcnt(0)
	v_mfma_f32_32x32x16_bf16 v[62:77], v[22:25], v[110:113], v[62:77]
	ds_read_b128 v[16:19], v162 offset:128
	ds_read_b128 v[22:25], v162 offset:6784
	s_waitcnt lgkmcnt(1)
	v_mfma_f32_32x32x16_bf16 v[46:61], v[16:19], v[114:117], v[46:61]
	s_waitcnt lgkmcnt(0)
	v_mfma_f32_32x32x16_bf16 v[62:77], v[22:25], v[114:117], v[62:77]
	ds_read_b128 v[16:19], v162 offset:160
	ds_read_b128 v[22:25], v162 offset:6816
	s_waitcnt lgkmcnt(0)
	s_barrier
	v_mfma_f32_32x32x16_bf16 v[46:61], v[16:19], v[118:121], v[46:61]
	v_mfma_f32_32x32x16_bf16 v[62:77], v[22:25], v[118:121], v[62:77]
	v_mov_b32_e32 v14, 0
	v_mov_b32_e32 v15, 0
	v_mov_b32_e32 v16, 0
	v_mov_b32_e32 v17, 0
	v_mov_b32_e32 v18, 0
	v_mov_b32_e32 v19, 0
	v_mov_b32_e32 v20, 0
	v_mov_b32_e32 v21, 0
	v_mov_b32_e32 v22, 0
	v_mov_b32_e32 v23, 0
	v_mov_b32_e32 v24, 0
	v_mov_b32_e32 v25, 0
	v_mov_b32_e32 v26, 0
	v_mov_b32_e32 v27, 0
	v_mov_b32_e32 v28, 0
	v_mov_b32_e32 v29, 0
	v_mov_b32_e32 v30, 0
	v_mov_b32_e32 v31, 0
	v_mov_b32_e32 v32, 0
	v_mov_b32_e32 v33, 0
	v_mov_b32_e32 v34, 0
	v_mov_b32_e32 v35, 0
	v_mov_b32_e32 v36, 0
	v_mov_b32_e32 v37, 0
	v_mov_b32_e32 v38, 0
	v_mov_b32_e32 v39, 0
	v_mov_b32_e32 v40, 0
	v_mov_b32_e32 v41, 0
	v_mov_b32_e32 v42, 0
	v_mov_b32_e32 v43, 0
	v_mov_b32_e32 v44, 0
	v_mov_b32_e32 v45, 0
	v_mov_b32_e32 v165, 0
	s_and_b32 s4, s3, 56
	s_lshl_b32 s4, s4, 19
	s_or_b32 s4, s4, s12
	s_add_u32 s54, s22, s4
	s_addc_u32 s55, s23, 0
	s_add_u32 s54, s54, 0x15a20000
	s_addc_u32 s55, s55, 0
	s_add_u32 s56, s22, s96
	s_addc_u32 s57, s23, 0
	s_add_u32 s56, s56, 0x12802000
	s_addc_u32 s57, s57, 0
	v_lshlrev_b32_e32 v226, 1, v148
	v_lshlrev_b32_e32 v227, 1, v12
	v_add_u32_e32 v227, 0x1ff0000, v227
	v_lshlrev_b32_e32 v228, 1, v150
	global_load_dwordx4 v[126:129], v226, s[54:55]
	s_and_saveexec_b64 s[4:5], s[6:7]
	s_cbranch_execz .Lm3_nokrp
	global_load_dwordx4 v[122:125], v228, s[56:57]
.Lm3_nokrp:
	s_or_b64 exec, exec, s[4:5]
	global_load_dwordx4 v[130:133], v227, s[54:55]
	s_add_u32 s54, s54, 0x10000
	s_addc_u32 s55, s55, 0
	s_add_u32 s56, s56, 0x1000
	s_addc_u32 s57, s57, 0
	ds_read_b128 v[134:137], v162 offset:13312
	ds_read_b128 v[138:141], v162 offset:19968
	ds_read_b128 v[142:145], v162 offset:13344
	ds_read_b128 v[168:171], v162 offset:20000
	ds_read_b128 v[172:175], v162 offset:13376
	ds_read_b128 v[178:181], v162 offset:20032
	ds_read_b128 v[182:185], v162 offset:13408
	ds_read_b128 v[186:189], v162 offset:20064
	ds_read_b128 v[206:209], v162 offset:13440
	ds_read_b128 v[210:213], v162 offset:20096
	ds_read_b128 v[214:217], v162 offset:13472
	ds_read_b128 v[248:251], v162 offset:20128
	v_max3_f32 v240, v46, v47, v48
	v_max3_f32 v241, v49, v50, v51
	v_max3_f32 v240, v240, v52, v53
	v_max3_f32 v241, v241, v54, v55
	v_max3_f32 v240, v240, v56, v57
	v_max3_f32 v241, v241, v58, v59
	v_max3_f32 v240, v240, v60, v61
	v_max3_f32 v241, v241, v62, v63
	v_max3_f32 v240, v240, v64, v65
	v_max3_f32 v241, v241, v66, v67
	v_max3_f32 v240, v240, v68, v69
	v_max3_f32 v241, v241, v70, v71
	v_max3_f32 v240, v240, v72, v73
	v_max3_f32 v241, v241, v74, v75
	v_max3_f32 v240, v240, v76, v77
	v_max_f32_e32 v240, v240, v241
	v_mov_b32_e32 v241, v240
	s_nop 1
	v_permlane32_swap_b32_e32 v240, v241
	v_max_f32_e32 v244, v240, v241
	v_mov_b32_e32 v164, v244
	v_sub_f32_e32 v190, 0, v244
	v_mov_b32_e32 v191, v190
	v_mov_b32_e32 v192, v190
	v_mov_b32_e32 v193, v190
	v_mov_b32_e32 v194, v190
	v_mov_b32_e32 v195, v190
	v_mov_b32_e32 v196, v190
	v_mov_b32_e32 v197, v190
	v_mov_b32_e32 v198, v190
	v_mov_b32_e32 v199, v190
	v_mov_b32_e32 v200, v190
	v_mov_b32_e32 v201, v190
	v_mov_b32_e32 v202, v190
	v_mov_b32_e32 v203, v190
	v_mov_b32_e32 v204, v190
	v_mov_b32_e32 v205, v190
	v_sub_f32_e32 v46, v46, v164
	v_sub_f32_e32 v47, v47, v164
	v_sub_f32_e32 v48, v48, v164
	v_sub_f32_e32 v49, v49, v164
	v_sub_f32_e32 v50, v50, v164
	v_sub_f32_e32 v51, v51, v164
	v_sub_f32_e32 v52, v52, v164
	v_sub_f32_e32 v53, v53, v164
	v_sub_f32_e32 v54, v54, v164
	v_sub_f32_e32 v55, v55, v164
	v_sub_f32_e32 v56, v56, v164
	v_sub_f32_e32 v57, v57, v164
	v_sub_f32_e32 v58, v58, v164
	v_sub_f32_e32 v59, v59, v164
	v_sub_f32_e32 v60, v60, v164
	v_sub_f32_e32 v61, v61, v164
	v_sub_f32_e32 v62, v62, v164
	v_sub_f32_e32 v63, v63, v164
	v_sub_f32_e32 v64, v64, v164
	v_sub_f32_e32 v65, v65, v164
	v_sub_f32_e32 v66, v66, v164
	v_sub_f32_e32 v67, v67, v164
	v_sub_f32_e32 v68, v68, v164
	v_sub_f32_e32 v69, v69, v164
	v_sub_f32_e32 v70, v70, v164
	v_sub_f32_e32 v71, v71, v164
	v_sub_f32_e32 v72, v72, v164
	v_sub_f32_e32 v73, v73, v164
	v_sub_f32_e32 v74, v74, v164
	v_sub_f32_e32 v75, v75, v164
	v_sub_f32_e32 v76, v76, v164
	v_sub_f32_e32 v77, v77, v164
	v_mov_b32_e32 v244, 0
	s_lshr_b32 s11, s33, 1
	s_mov_b32 s10, 0
	s_cmp_le_u32 s35, 4
	s_cbranch_scc1 .Lm3_tail0

.Lm3_nokwa:
	s_or_b64 exec, exec, s[4:5]
	ds_write_b128 v159, v[130:133] offset:34816
	v_mfma_f32_32x32x16_bf16 v[94:109], v[210:213], v[114:117], v[94:109]
	v_add_f32_e32 v243, v243, v61
	v_exp_f32_e32 v70, v70
	v_exp_f32_e32 v71, v71
	v_exp_f32_e32 v72, v72
	v_mfma_f32_32x32x16_bf16 v[78:93], v[214:217], v[118:121], v[78:93]
	v_exp_f32_e32 v73, v73
	v_exp_f32_e32 v74, v74
	v_exp_f32_e32 v75, v75
	v_exp_f32_e32 v76, v76
	v_mfma_f32_32x32x16_bf16 v[94:109], v[248:251], v[118:121], v[94:109]
	v_exp_f32_e32 v77, v77
	v_add_f32_e32 v238, v238, v62
	v_add_f32_e32 v239, v239, v63
	v_add_f32_e32 v242, v242, v64
	v_add_f32_e32 v243, v243, v65
	s_waitcnt lgkmcnt(0)
	s_barrier
	ds_read_b128 v[206:209], v162 offset:128
	ds_read_b128 v[210:213], v162 offset:6784
	ds_read_b128 v[214:217], v162 offset:160
	ds_read_b128 v[248:251], v162 offset:6816
	v_mfma_f32_32x32x16_bf16 v[14:29], v[134:137], v[152:155], v[14:29]
	ds_read_b128 v[134:137], v162
	v_cvt_pk_bf16_f32 v222, v54, v55
	v_cvt_pk_bf16_f32 v223, v56, v57
	v_cvt_pk_bf16_f32 v224, v58, v59
	v_cvt_pk_bf16_f32 v225, v60, v61
	v_cvt_pk_bf16_f32 v230, v62, v63
	v_cvt_pk_bf16_f32 v231, v64, v65
	v_mfma_f32_32x32x16_bf16 v[30:45], v[138:141], v[152:155], v[30:45]
	ds_read_b128 v[138:141], v162 offset:6656
	global_load_dwordx4 v[126:129], v226, s[54:55]
	s_and_saveexec_b64 s[4:5], s[6:7]
	s_cbranch_execz .Lm3_nokra
	global_load_dwordx4 v[122:125], v228, s[56:57]
.Lm3_nokra:
	s_or_b64 exec, exec, s[4:5]
	v_cvt_pk_bf16_f32 v232, v66, v67
	v_cvt_pk_bf16_f32 v233, v68, v69
	v_add_f32_e32 v238, v238, v66
	v_add_f32_e32 v239, v239, v67
	v_add_f32_e32 v242, v242, v68
	v_add_f32_e32 v243, v243, v69
	v_mfma_f32_32x32x16_bf16 v[14:29], v[142:145], v[222:225], v[14:29]
	ds_read_b128 v[142:145], v162 offset:32
	v_cvt_pk_bf16_f32 v234, v70, v71
	v_cvt_pk_bf16_f32 v235, v72, v73
	v_cvt_pk_bf16_f32 v236, v74, v75
	v_cvt_pk_bf16_f32 v237, v76, v77
	v_add_f32_e32 v238, v238, v70
	v_add_f32_e32 v239, v239, v71
	v_mfma_f32_32x32x16_bf16 v[30:45], v[168:171], v[222:225], v[30:45]
	ds_read_b128 v[168:171], v162 offset:6688
	v_add_f32_e32 v242, v242, v72
	v_add_f32_e32 v243, v243, v73
	v_add_f32_e32 v238, v238, v74
	v_add_f32_e32 v239, v239, v75
	v_add_f32_e32 v242, v242, v76
	v_add_f32_e32 v243, v243, v77
	v_add_f32_e32 v238, v238, v239
	v_mfma_f32_32x32x16_bf16 v[14:29], v[172:175], v[230:233], v[14:29]
	ds_read_b128 v[172:175], v162 offset:64
	v_add_f32_e32 v242, v242, v243
	v_add_f32_e32 v238, v238, v242
	v_add_f32_e32 v165, v165, v238
	v_max3_f32 v240, v78, v79, v80
	v_max3_f32 v241, v81, v82, v83
	v_max3_f32 v240, v240, v84, v85
	v_mfma_f32_32x32x16_bf16 v[30:45], v[178:181], v[230:233], v[30:45]
	ds_read_b128 v[178:181], v162 offset:6720
	global_load_dwordx4 v[130:133], v227, s[54:55]
	v_max3_f32 v241, v241, v86, v87
	v_max3_f32 v240, v240, v88, v89
	v_max3_f32 v241, v241, v90, v91
	v_max3_f32 v240, v240, v92, v93
	v_max3_f32 v241, v241, v94, v95
	v_max3_f32 v240, v240, v96, v97
	v_mfma_f32_32x32x16_bf16 v[14:29], v[182:185], v[234:237], v[14:29]
	ds_read_b128 v[182:185], v162 offset:96
	v_max3_f32 v241, v241, v98, v99
	v_max3_f32 v240, v240, v100, v101
	v_max3_f32 v241, v241, v102, v103
	v_max3_f32 v240, v240, v104, v105
	v_max3_f32 v241, v241, v106, v107
	v_mfma_f32_32x32x16_bf16 v[30:45], v[186:189], v[234:237], v[30:45]
	ds_read_b128 v[186:189], v162 offset:6752
	v_max3_f32 v240, v240, v108, v109
	v_max_f32_e32 v240, v240, v241
	v_mov_b32_e32 v241, v240
	s_nop 1
	v_permlane32_swap_b32_e32 v240, v241
	v_max_f32_e32 v244, v240, v241
	s_add_u32 s54, s54, 0x10000
	s_addc_u32 s55, s55, 0
	s_add_u32 s56, s56, 0x1000
	s_addc_u32 s57, s57, 0
	v_cmp_lt_f32_e32 vcc, 0x41800000, v244
	s_cbranch_vccnz .Lm3_rescb

.Lm3_nokwb:
	s_or_b64 exec, exec, s[4:5]
	ds_write_b128 v159, v[130:133] offset:26624
	v_mfma_f32_32x32x16_bf16 v[62:77], v[210:213], v[114:117], v[62:77]
	v_add_f32_e32 v243, v243, v93
	v_exp_f32_e32 v102, v102
	v_exp_f32_e32 v103, v103
	v_exp_f32_e32 v104, v104
	v_mfma_f32_32x32x16_bf16 v[46:61], v[214:217], v[118:121], v[46:61]
	v_exp_f32_e32 v105, v105
	v_exp_f32_e32 v106, v106
	v_exp_f32_e32 v107, v107
	v_exp_f32_e32 v108, v108
	v_mfma_f32_32x32x16_bf16 v[62:77], v[248:251], v[118:121], v[62:77]
	v_exp_f32_e32 v109, v109
	v_add_f32_e32 v238, v238, v94
	v_add_f32_e32 v239, v239, v95
	v_add_f32_e32 v242, v242, v96
	v_add_f32_e32 v243, v243, v97
	s_waitcnt lgkmcnt(0)
	s_barrier
	ds_read_b128 v[206:209], v162 offset:13440
	ds_read_b128 v[210:213], v162 offset:20096
	ds_read_b128 v[214:217], v162 offset:13472
	ds_read_b128 v[248:251], v162 offset:20128
	v_mfma_f32_32x32x16_bf16 v[14:29], v[134:137], v[152:155], v[14:29]
	ds_read_b128 v[134:137], v162 offset:13312
	v_cvt_pk_bf16_f32 v222, v86, v87
	v_cvt_pk_bf16_f32 v223, v88, v89
	v_cvt_pk_bf16_f32 v224, v90, v91
	v_cvt_pk_bf16_f32 v225, v92, v93
	v_cvt_pk_bf16_f32 v230, v94, v95
	v_cvt_pk_bf16_f32 v231, v96, v97
	v_mfma_f32_32x32x16_bf16 v[30:45], v[138:141], v[152:155], v[30:45]
	ds_read_b128 v[138:141], v162 offset:19968
	global_load_dwordx4 v[126:129], v226, s[54:55]
	s_and_saveexec_b64 s[4:5], s[6:7]
	s_cbranch_execz .Lm3_nokrb
	global_load_dwordx4 v[122:125], v228, s[56:57]
.Lm3_nokrb:
	s_or_b64 exec, exec, s[4:5]
	v_cvt_pk_bf16_f32 v232, v98, v99
	v_cvt_pk_bf16_f32 v233, v100, v101
	v_add_f32_e32 v238, v238, v98
	v_add_f32_e32 v239, v239, v99
	v_add_f32_e32 v242, v242, v100
	v_add_f32_e32 v243, v243, v101
	v_mfma_f32_32x32x16_bf16 v[14:29], v[142:145], v[222:225], v[14:29]
	ds_read_b128 v[142:145], v162 offset:13344
	v_cvt_pk_bf16_f32 v234, v102, v103
	v_cvt_pk_bf16_f32 v235, v104, v105
	v_cvt_pk_bf16_f32 v236, v106, v107
	v_cvt_pk_bf16_f32 v237, v108, v109
	v_add_f32_e32 v238, v238, v102
	v_add_f32_e32 v239, v239, v103
	v_mfma_f32_32x32x16_bf16 v[30:45], v[168:171], v[222:225], v[30:45]
	ds_read_b128 v[168:171], v162 offset:20000
	v_add_f32_e32 v242, v242, v104
	v_add_f32_e32 v243, v243, v105
	v_add_f32_e32 v238, v238, v106
	v_add_f32_e32 v239, v239, v107
	v_add_f32_e32 v242, v242, v108
	v_add_f32_e32 v243, v243, v109
	v_add_f32_e32 v238, v238, v239
	v_mfma_f32_32x32x16_bf16 v[14:29], v[172:175], v[230:233], v[14:29]
	ds_read_b128 v[172:175], v162 offset:13376
	v_add_f32_e32 v242, v242, v243
	v_add_f32_e32 v238, v238, v242
	v_add_f32_e32 v165, v165, v238
	v_max3_f32 v240, v46, v47, v48
	v_max3_f32 v241, v49, v50, v51
	v_max3_f32 v240, v240, v52, v53
	v_mfma_f32_32x32x16_bf16 v[30:45], v[178:181], v[230:233], v[30:45]
	ds_read_b128 v[178:181], v162 offset:20032
	global_load_dwordx4 v[130:133], v227, s[54:55]
	v_max3_f32 v241, v241, v54, v55
	v_max3_f32 v240, v240, v56, v57
	v_max3_f32 v241, v241, v58, v59
	v_max3_f32 v240, v240, v60, v61
	v_max3_f32 v241, v241, v62, v63
	v_max3_f32 v240, v240, v64, v65
	v_mfma_f32_32x32x16_bf16 v[14:29], v[182:185], v[234:237], v[14:29]
	ds_read_b128 v[182:185], v162 offset:13408
	v_max3_f32 v241, v241, v66, v67
	v_max3_f32 v240, v240, v68, v69
	v_max3_f32 v241, v241, v70, v71
	v_max3_f32 v240, v240, v72, v73
	v_max3_f32 v241, v241, v74, v75
	v_mfma_f32_32x32x16_bf16 v[30:45], v[186:189], v[234:237], v[30:45]
	ds_read_b128 v[186:189], v162 offset:20064
	v_max3_f32 v240, v240, v76, v77
	v_max_f32_e32 v240, v240, v241
	v_mov_b32_e32 v241, v240
	s_nop 1
	v_permlane32_swap_b32_e32 v240, v241
	v_max_f32_e32 v244, v240, v241
	s_add_u32 s54, s54, 0x10000
	s_addc_u32 s55, s55, 0
	s_add_u32 s56, s56, 0x1000
	s_addc_u32 s57, s57, 0
	s_add_i32 s10, s10, 2
	s_add_i32 s4, s10, 4
	s_cmp_lt_u32 s4, s35
	s_cbranch_scc1 .Lm3_loop
.Lm3_tail0:
	s_cmp_gt_u32 s11, 0
	s_cbranch_scc1 .Lm3_t0_full
	s_cmp_eq_u32 s11, 0
	s_cbranch_scc1 .Lm3_t0_last
	s_waitcnt lgkmcnt(0)
	s_waitcnt vmcnt(0)
	ds_write_b128 v158, v[126:129]
	s_and_saveexec_b64 s[4:5], s[6:7]
	s_cbranch_execz .Lm3_nokwt0i
	ds_write_b128 v163, v[122:125] offset:128
.Lm3_nokwt0i:
	s_or_b64 exec, exec, s[4:5]
	ds_write_b128 v159, v[130:133] offset:34816
	s_waitcnt lgkmcnt(0)
	s_barrier
	global_load_dwordx4 v[126:129], v226, s[54:55]
	s_and_saveexec_b64 s[4:5], s[6:7]
	s_cbranch_execz .Lm3_nokrt0i
	global_load_dwordx4 v[122:125], v228, s[56:57]
.Lm3_nokrt0i:
	s_or_b64 exec, exec, s[4:5]
	global_load_dwordx4 v[130:133], v227, s[54:55]
	s_add_u32 s54, s54, 0x10000
	s_addc_u32 s55, s55, 0
	s_add_u32 s56, s56, 0x1000
	s_addc_u32 s57, s57, 0
	s_branch .Lm3_tail1

.Lm3_resc_rett0l:
	s_waitcnt lgkmcnt(0)
	ds_read_b64_tr_b16 v[134:135], v161 offset:26624
	ds_read_b64_tr_b16 v[136:137], v161 offset:27136
	ds_read_b64_tr_b16 v[138:139], v161 offset:30720
	ds_read_b64_tr_b16 v[140:141], v161 offset:31232
	ds_read_b64_tr_b16 v[142:143], v161 offset:27648
	ds_read_b64_tr_b16 v[144:145], v161 offset:28160
	ds_read_b64_tr_b16 v[168:169], v161 offset:31744
	ds_read_b64_tr_b16 v[170:171], v161 offset:32256
	ds_read_b64_tr_b16 v[172:173], v161 offset:28672
	ds_read_b64_tr_b16 v[174:175], v161 offset:29184
	ds_read_b64_tr_b16 v[178:179], v161 offset:32768
	ds_read_b64_tr_b16 v[180:181], v161 offset:33280
	ds_read_b64_tr_b16 v[182:183], v161 offset:29696
	ds_read_b64_tr_b16 v[184:185], v161 offset:30208
	v_exp_f32_e32 v46, v46
	v_exp_f32_e32 v47, v47
	v_exp_f32_e32 v48, v48
	v_exp_f32_e32 v49, v49
	v_exp_f32_e32 v50, v50
	v_exp_f32_e32 v51, v51
	v_exp_f32_e32 v52, v52
	v_exp_f32_e32 v53, v53
	v_cvt_pk_bf16_f32 v152, v46, v47
	v_cvt_pk_bf16_f32 v153, v48, v49
	v_cvt_pk_bf16_f32 v154, v50, v51
	v_cvt_pk_bf16_f32 v155, v52, v53
	v_exp_f32_e32 v54, v54
	v_exp_f32_e32 v55, v55
	v_exp_f32_e32 v56, v56
	v_exp_f32_e32 v57, v57
	v_exp_f32_e32 v58, v58
	v_exp_f32_e32 v59, v59
	v_exp_f32_e32 v60, v60
	v_exp_f32_e32 v61, v61
	v_add_f32_e32 v238, v46, v47
	v_add_f32_e32 v239, v48, v49
	v_add_f32_e32 v242, v50, v51
	v_add_f32_e32 v243, v52, v53
	v_exp_f32_e32 v62, v62
	v_exp_f32_e32 v63, v63
	v_exp_f32_e32 v64, v64
	v_exp_f32_e32 v65, v65
	v_exp_f32_e32 v66, v66
	v_exp_f32_e32 v67, v67
	v_exp_f32_e32 v68, v68
	v_exp_f32_e32 v69, v69
	v_add_f32_e32 v238, v238, v54
	v_add_f32_e32 v239, v239, v55
	v_add_f32_e32 v242, v242, v56
	v_add_f32_e32 v243, v243, v57
	v_add_f32_e32 v238, v238, v58
	v_add_f32_e32 v239, v239, v59
	v_add_f32_e32 v242, v242, v60
	v_add_f32_e32 v243, v243, v61
	v_exp_f32_e32 v70, v70
	v_exp_f32_e32 v71, v71
	v_exp_f32_e32 v72, v72
	v_exp_f32_e32 v73, v73
	v_exp_f32_e32 v74, v74
	v_exp_f32_e32 v75, v75
	v_exp_f32_e32 v76, v76
	v_exp_f32_e32 v77, v77
	v_add_f32_e32 v238, v238, v62
	v_add_f32_e32 v239, v239, v63
	v_add_f32_e32 v242, v242, v64
	v_add_f32_e32 v243, v243, v65
	s_waitcnt lgkmcnt(8)
	ds_read_b64_tr_b16 v[186:187], v161 offset:33792
	ds_read_b64_tr_b16 v[188:189], v161 offset:34304
	s_waitcnt vmcnt(0)
	ds_write_b128 v158, v[126:129]
	s_and_saveexec_b64 s[4:5], s[6:7]
	s_cbranch_execz .Lm3_nokwt0l
	ds_write_b128 v163, v[122:125] offset:128
.Lm3_nokwt0l:
	s_or_b64 exec, exec, s[4:5]
	ds_write_b128 v159, v[130:133] offset:34816
	s_waitcnt lgkmcnt(0)
	s_barrier
	v_mfma_f32_32x32x16_bf16 v[14:29], v[134:137], v[152:155], v[14:29]
	v_cvt_pk_bf16_f32 v222, v54, v55
	v_cvt_pk_bf16_f32 v223, v56, v57
	v_cvt_pk_bf16_f32 v224, v58, v59
	v_mfma_f32_32x32x16_bf16 v[30:45], v[138:141], v[152:155], v[30:45]
	global_load_dwordx4 v[126:129], v226, s[54:55]
	s_and_saveexec_b64 s[4:5], s[6:7]
	s_cbranch_execz .Lm3_nokrt0l
	global_load_dwordx4 v[122:125], v228, s[56:57]
.Lm3_nokrt0l:
	s_or_b64 exec, exec, s[4:5]
	v_cvt_pk_bf16_f32 v225, v60, v61
	v_cvt_pk_bf16_f32 v230, v62, v63
	v_cvt_pk_bf16_f32 v231, v64, v65
	v_mfma_f32_32x32x16_bf16 v[14:29], v[142:145], v[222:225], v[14:29]
	v_cvt_pk_bf16_f32 v232, v66, v67
	v_cvt_pk_bf16_f32 v233, v68, v69
	v_add_f32_e32 v238, v238, v66
	v_mfma_f32_32x32x16_bf16 v[30:45], v[168:171], v[222:225], v[30:45]
	v_add_f32_e32 v239, v239, v67
	v_add_f32_e32 v242, v242, v68
	v_add_f32_e32 v243, v243, v69
	v_cvt_pk_bf16_f32 v234, v70, v71
	v_mfma_f32_32x32x16_bf16 v[14:29], v[172:175], v[230:233], v[14:29]
	v_cvt_pk_bf16_f32 v235, v72, v73
	v_cvt_pk_bf16_f32 v236, v74, v75
	v_cvt_pk_bf16_f32 v237, v76, v77
	v_mfma_f32_32x32x16_bf16 v[30:45], v[178:181], v[230:233], v[30:45]
	global_load_dwordx4 v[130:133], v227, s[54:55]
	v_add_f32_e32 v238, v238, v70
	v_add_f32_e32 v239, v239, v71
	v_add_f32_e32 v242, v242, v72
	v_add_f32_e32 v243, v243, v73
	v_mfma_f32_32x32x16_bf16 v[14:29], v[182:185], v[234:237], v[14:29]
	v_add_f32_e32 v238, v238, v74
	v_add_f32_e32 v239, v239, v75
	v_add_f32_e32 v242, v242, v76
	v_add_f32_e32 v243, v243, v77
	v_mfma_f32_32x32x16_bf16 v[30:45], v[186:189], v[234:237], v[30:45]
	v_add_f32_e32 v238, v238, v239
	v_add_f32_e32 v242, v242, v243
	v_add_f32_e32 v238, v238, v242
	v_add_f32_e32 v165, v165, v238
	s_add_u32 s54, s54, 0x10000
	s_addc_u32 s55, s55, 0
	s_add_u32 s56, s56, 0x1000
	s_addc_u32 s57, s57, 0
	s_branch .Lm3_tail1

.Lm3_nokrt0f:
	s_or_b64 exec, exec, s[4:5]
	v_cvt_pk_bf16_f32 v232, v66, v67
	v_cvt_pk_bf16_f32 v233, v68, v69
	v_add_f32_e32 v238, v238, v66
	v_add_f32_e32 v239, v239, v67
	v_add_f32_e32 v242, v242, v68
	v_add_f32_e32 v243, v243, v69
	v_mfma_f32_32x32x16_bf16 v[14:29], v[142:145], v[222:225], v[14:29]
	ds_read_b128 v[142:145], v162 offset:32
	v_cvt_pk_bf16_f32 v234, v70, v71
	v_cvt_pk_bf16_f32 v235, v72, v73
	v_cvt_pk_bf16_f32 v236, v74, v75
	v_cvt_pk_bf16_f32 v237, v76, v77
	v_add_f32_e32 v238, v238, v70
	v_add_f32_e32 v239, v239, v71
	v_mfma_f32_32x32x16_bf16 v[30:45], v[168:171], v[222:225], v[30:45]
	ds_read_b128 v[168:171], v162 offset:6688
	v_add_f32_e32 v242, v242, v72
	v_add_f32_e32 v243, v243, v73
	v_add_f32_e32 v238, v238, v74
	v_add_f32_e32 v239, v239, v75
	v_add_f32_e32 v242, v242, v76
	v_add_f32_e32 v243, v243, v77
	v_add_f32_e32 v238, v238, v239
	v_mfma_f32_32x32x16_bf16 v[14:29], v[172:175], v[230:233], v[14:29]
	ds_read_b128 v[172:175], v162 offset:64
	v_add_f32_e32 v242, v242, v243
	v_add_f32_e32 v238, v238, v242
	v_add_f32_e32 v165, v165, v238
	v_max3_f32 v240, v78, v79, v80
	v_max3_f32 v241, v81, v82, v83
	v_max3_f32 v240, v240, v84, v85
	v_mfma_f32_32x32x16_bf16 v[30:45], v[178:181], v[230:233], v[30:45]
	ds_read_b128 v[178:181], v162 offset:6720
	global_load_dwordx4 v[130:133], v227, s[54:55]
	v_max3_f32 v241, v241, v86, v87
	v_max3_f32 v240, v240, v88, v89
	v_max3_f32 v241, v241, v90, v91
	v_max3_f32 v240, v240, v92, v93
	v_max3_f32 v241, v241, v94, v95
	v_max3_f32 v240, v240, v96, v97
	v_mfma_f32_32x32x16_bf16 v[14:29], v[182:185], v[234:237], v[14:29]
	ds_read_b128 v[182:185], v162 offset:96
	v_max3_f32 v241, v241, v98, v99
	v_max3_f32 v240, v240, v100, v101
	v_max3_f32 v241, v241, v102, v103
	v_max3_f32 v240, v240, v104, v105
	v_max3_f32 v241, v241, v106, v107
	v_mfma_f32_32x32x16_bf16 v[30:45], v[186:189], v[234:237], v[30:45]
	ds_read_b128 v[186:189], v162 offset:6752
	v_max3_f32 v240, v240, v108, v109
	v_max_f32_e32 v240, v240, v241
	v_mov_b32_e32 v241, v240
	s_nop 1
	v_permlane32_swap_b32_e32 v240, v241
	v_max_f32_e32 v244, v240, v241
	s_add_u32 s54, s54, 0x10000
	s_addc_u32 s55, s55, 0
	s_add_u32 s56, s56, 0x1000
	s_addc_u32 s57, s57, 0
.Lm3_tail1:
	s_cmp_gt_u32 s11, 1
	s_cbranch_scc1 .Lm3_t1_full
	s_cmp_eq_u32 s11, 1
	s_cbranch_scc1 .Lm3_t1_last
	s_waitcnt lgkmcnt(0)
	s_waitcnt vmcnt(0)
	ds_write_b128 v158, v[126:129] offset:13312
	s_and_saveexec_b64 s[4:5], s[6:7]
	s_cbranch_execz .Lm3_nokwt1i
	ds_write_b128 v163, v[122:125] offset:13440
.Lm3_nokwt1i:
	s_or_b64 exec, exec, s[4:5]
	ds_write_b128 v159, v[130:133] offset:26624
	s_waitcnt lgkmcnt(0)
	s_barrier
	global_load_dwordx4 v[130:133], v227, s[54:55]
	s_add_u32 s54, s54, 0x10000
	s_addc_u32 s55, s55, 0
	s_add_u32 s56, s56, 0x1000
	s_addc_u32 s57, s57, 0
	s_branch .Lm3_tail2

.Lm3_resc_rett1l:
	s_waitcnt lgkmcnt(0)
	ds_read_b64_tr_b16 v[134:135], v161 offset:34816
	ds_read_b64_tr_b16 v[136:137], v161 offset:35328
	ds_read_b64_tr_b16 v[138:139], v161 offset:38912
	ds_read_b64_tr_b16 v[140:141], v161 offset:39424
	ds_read_b64_tr_b16 v[142:143], v161 offset:35840
	ds_read_b64_tr_b16 v[144:145], v161 offset:36352
	ds_read_b64_tr_b16 v[168:169], v161 offset:39936
	ds_read_b64_tr_b16 v[170:171], v161 offset:40448
	ds_read_b64_tr_b16 v[172:173], v161 offset:36864
	ds_read_b64_tr_b16 v[174:175], v161 offset:37376
	ds_read_b64_tr_b16 v[178:179], v161 offset:40960
	ds_read_b64_tr_b16 v[180:181], v161 offset:41472
	ds_read_b64_tr_b16 v[182:183], v161 offset:37888
	ds_read_b64_tr_b16 v[184:185], v161 offset:38400
	v_exp_f32_e32 v78, v78
	v_exp_f32_e32 v79, v79
	v_exp_f32_e32 v80, v80
	v_exp_f32_e32 v81, v81
	v_exp_f32_e32 v82, v82
	v_exp_f32_e32 v83, v83
	v_exp_f32_e32 v84, v84
	v_exp_f32_e32 v85, v85
	v_cvt_pk_bf16_f32 v152, v78, v79
	v_cvt_pk_bf16_f32 v153, v80, v81
	v_cvt_pk_bf16_f32 v154, v82, v83
	v_cvt_pk_bf16_f32 v155, v84, v85
	v_exp_f32_e32 v86, v86
	v_exp_f32_e32 v87, v87
	v_exp_f32_e32 v88, v88
	v_exp_f32_e32 v89, v89
	v_exp_f32_e32 v90, v90
	v_exp_f32_e32 v91, v91
	v_exp_f32_e32 v92, v92
	v_exp_f32_e32 v93, v93
	v_add_f32_e32 v238, v78, v79
	v_add_f32_e32 v239, v80, v81
	v_add_f32_e32 v242, v82, v83
	v_add_f32_e32 v243, v84, v85
	v_exp_f32_e32 v94, v94
	v_exp_f32_e32 v95, v95
	v_exp_f32_e32 v96, v96
	v_exp_f32_e32 v97, v97
	v_exp_f32_e32 v98, v98
	v_exp_f32_e32 v99, v99
	v_exp_f32_e32 v100, v100
	v_exp_f32_e32 v101, v101
	v_add_f32_e32 v238, v238, v86
	v_add_f32_e32 v239, v239, v87
	v_add_f32_e32 v242, v242, v88
	v_add_f32_e32 v243, v243, v89
	v_add_f32_e32 v238, v238, v90
	v_add_f32_e32 v239, v239, v91
	v_add_f32_e32 v242, v242, v92
	v_add_f32_e32 v243, v243, v93
	v_exp_f32_e32 v102, v102
	v_exp_f32_e32 v103, v103
	v_exp_f32_e32 v104, v104
	v_exp_f32_e32 v105, v105
	v_exp_f32_e32 v106, v106
	v_exp_f32_e32 v107, v107
	v_exp_f32_e32 v108, v108
	v_exp_f32_e32 v109, v109
	v_add_f32_e32 v238, v238, v94
	v_add_f32_e32 v239, v239, v95
	v_add_f32_e32 v242, v242, v96
	v_add_f32_e32 v243, v243, v97
	s_waitcnt lgkmcnt(8)
	ds_read_b64_tr_b16 v[186:187], v161 offset:41984
	ds_read_b64_tr_b16 v[188:189], v161 offset:42496
	s_waitcnt vmcnt(0)
	ds_write_b128 v158, v[126:129] offset:13312
	s_and_saveexec_b64 s[4:5], s[6:7]
	s_cbranch_execz .Lm3_nokwt1l
	ds_write_b128 v163, v[122:125] offset:13440
.Lm3_nokwt1l:
	s_or_b64 exec, exec, s[4:5]
	ds_write_b128 v159, v[130:133] offset:26624
	s_waitcnt lgkmcnt(0)
	s_barrier
	v_mfma_f32_32x32x16_bf16 v[14:29], v[134:137], v[152:155], v[14:29]
	v_cvt_pk_bf16_f32 v222, v86, v87
	v_cvt_pk_bf16_f32 v223, v88, v89
	v_cvt_pk_bf16_f32 v224, v90, v91
	v_mfma_f32_32x32x16_bf16 v[30:45], v[138:141], v[152:155], v[30:45]
	v_cvt_pk_bf16_f32 v225, v92, v93
	v_cvt_pk_bf16_f32 v230, v94, v95
	v_cvt_pk_bf16_f32 v231, v96, v97
	v_mfma_f32_32x32x16_bf16 v[14:29], v[142:145], v[222:225], v[14:29]
	v_cvt_pk_bf16_f32 v232, v98, v99
	v_cvt_pk_bf16_f32 v233, v100, v101
	v_add_f32_e32 v238, v238, v98
	v_mfma_f32_32x32x16_bf16 v[30:45], v[168:171], v[222:225], v[30:45]
	v_add_f32_e32 v239, v239, v99
	v_add_f32_e32 v242, v242, v100
	v_add_f32_e32 v243, v243, v101
	v_cvt_pk_bf16_f32 v234, v102, v103
	v_mfma_f32_32x32x16_bf16 v[14:29], v[172:175], v[230:233], v[14:29]
	v_cvt_pk_bf16_f32 v235, v104, v105
	v_cvt_pk_bf16_f32 v236, v106, v107
	v_cvt_pk_bf16_f32 v237, v108, v109
	v_mfma_f32_32x32x16_bf16 v[30:45], v[178:181], v[230:233], v[30:45]
	global_load_dwordx4 v[130:133], v227, s[54:55]
	v_add_f32_e32 v238, v238, v102
	v_add_f32_e32 v239, v239, v103
	v_add_f32_e32 v242, v242, v104
	v_add_f32_e32 v243, v243, v105
	v_mfma_f32_32x32x16_bf16 v[14:29], v[182:185], v[234:237], v[14:29]
	v_add_f32_e32 v238, v238, v106
	v_add_f32_e32 v239, v239, v107
	v_add_f32_e32 v242, v242, v108
	v_add_f32_e32 v243, v243, v109
	v_mfma_f32_32x32x16_bf16 v[30:45], v[186:189], v[234:237], v[30:45]
	v_add_f32_e32 v238, v238, v239
	v_add_f32_e32 v242, v242, v243
	v_add_f32_e32 v238, v238, v242
	v_add_f32_e32 v165, v165, v238
	s_add_u32 s54, s54, 0x10000
	s_addc_u32 s55, s55, 0
	s_add_u32 s56, s56, 0x1000
	s_addc_u32 s57, s57, 0
	s_branch .Lm3_tail2
.Lm3_t1_full:
	v_cmp_lt_f32_e32 vcc, 0x41800000, v244
	s_cbranch_vccnz .Lm3_resct1f
.Lm3_resc_rett1f:
	s_waitcnt lgkmcnt(7)
	v_mfma_f32_32x32x16_bf16 v[46:61], v[134:137], v[0:3], v[190:205]
	ds_read_b64_tr_b16 v[134:135], v161 offset:34816
	ds_read_b64_tr_b16 v[136:137], v161 offset:35328
	v_exp_f32_e32 v78, v78
	v_exp_f32_e32 v79, v79
	v_exp_f32_e32 v80, v80
	v_exp_f32_e32 v81, v81
	s_waitcnt lgkmcnt(8)
	v_mfma_f32_32x32x16_bf16 v[62:77], v[138:141], v[0:3], v[190:205]
	ds_read_b64_tr_b16 v[138:139], v161 offset:38912
	ds_read_b64_tr_b16 v[140:141], v161 offset:39424
	v_exp_f32_e32 v82, v82
	v_exp_f32_e32 v83, v83
	v_exp_f32_e32 v84, v84
	v_exp_f32_e32 v85, v85
	s_waitcnt lgkmcnt(9)
	v_mfma_f32_32x32x16_bf16 v[46:61], v[142:145], v[4:7], v[46:61]
	ds_read_b64_tr_b16 v[142:143], v161 offset:35840
	ds_read_b64_tr_b16 v[144:145], v161 offset:36352
	v_cvt_pk_bf16_f32 v152, v78, v79
	v_cvt_pk_bf16_f32 v153, v80, v81
	v_cvt_pk_bf16_f32 v154, v82, v83
	v_cvt_pk_bf16_f32 v155, v84, v85
	s_waitcnt lgkmcnt(10)
	v_mfma_f32_32x32x16_bf16 v[62:77], v[168:171], v[4:7], v[62:77]
	ds_read_b64_tr_b16 v[168:169], v161 offset:39936
	ds_read_b64_tr_b16 v[170:171], v161 offset:40448
	v_exp_f32_e32 v86, v86
	v_exp_f32_e32 v87, v87
	v_exp_f32_e32 v88, v88
	v_exp_f32_e32 v89, v89
	s_waitcnt lgkmcnt(11)
	v_mfma_f32_32x32x16_bf16 v[46:61], v[172:175], v[8:11], v[46:61]
	ds_read_b64_tr_b16 v[172:173], v161 offset:36864
	ds_read_b64_tr_b16 v[174:175], v161 offset:37376
	v_exp_f32_e32 v90, v90
	v_exp_f32_e32 v91, v91
	v_exp_f32_e32 v92, v92
	s_waitcnt lgkmcnt(12)
	v_mfma_f32_32x32x16_bf16 v[62:77], v[178:181], v[8:11], v[62:77]
	ds_read_b64_tr_b16 v[178:179], v161 offset:40960
	ds_read_b64_tr_b16 v[180:181], v161 offset:41472
	v_exp_f32_e32 v93, v93
	v_add_f32_e32 v238, v78, v79
	v_add_f32_e32 v239, v80, v81
	v_add_f32_e32 v242, v82, v83
	v_add_f32_e32 v243, v84, v85
	v_exp_f32_e32 v94, v94
	s_waitcnt lgkmcnt(13)
	v_mfma_f32_32x32x16_bf16 v[46:61], v[182:185], v[110:113], v[46:61]
	ds_read_b64_tr_b16 v[182:183], v161 offset:37888
	ds_read_b64_tr_b16 v[184:185], v161 offset:38400
	v_exp_f32_e32 v95, v95
	v_exp_f32_e32 v96, v96
	v_exp_f32_e32 v97, v97
	v_exp_f32_e32 v98, v98
	s_waitcnt lgkmcnt(14)
	v_mfma_f32_32x32x16_bf16 v[62:77], v[186:189], v[110:113], v[62:77]
	s_waitcnt lgkmcnt(13)
	ds_read_b64_tr_b16 v[186:187], v161 offset:41984
	ds_read_b64_tr_b16 v[188:189], v161 offset:42496
	v_exp_f32_e32 v99, v99
	v_exp_f32_e32 v100, v100
	v_exp_f32_e32 v101, v101
	v_mfma_f32_32x32x16_bf16 v[46:61], v[206:209], v[114:117], v[46:61]
	v_add_f32_e32 v238, v238, v86
	v_add_f32_e32 v239, v239, v87
	v_add_f32_e32 v242, v242, v88
	v_add_f32_e32 v243, v243, v89
	v_add_f32_e32 v238, v238, v90
	v_add_f32_e32 v239, v239, v91
	v_add_f32_e32 v242, v242, v92
	s_waitcnt lgkmcnt(8)
	s_waitcnt vmcnt(0)
	ds_write_b128 v158, v[126:129] offset:13312
	s_and_saveexec_b64 s[4:5], s[6:7]
	s_cbranch_execz .Lm3_nokwt1f
	ds_write_b128 v163, v[122:125] offset:13440
.Lm3_nokwt1f:
	s_or_b64 exec, exec, s[4:5]
	ds_write_b128 v159, v[130:133] offset:26624
	v_mfma_f32_32x32x16_bf16 v[62:77], v[210:213], v[114:117], v[62:77]
	v_add_f32_e32 v243, v243, v93
	v_exp_f32_e32 v102, v102
	v_exp_f32_e32 v103, v103
	v_exp_f32_e32 v104, v104
	v_mfma_f32_32x32x16_bf16 v[46:61], v[214:217], v[118:121], v[46:61]
	v_exp_f32_e32 v105, v105
	v_exp_f32_e32 v106, v106
	v_exp_f32_e32 v107, v107
	v_exp_f32_e32 v108, v108
	v_mfma_f32_32x32x16_bf16 v[62:77], v[248:251], v[118:121], v[62:77]
	v_exp_f32_e32 v109, v109
	v_add_f32_e32 v238, v238, v94
	v_add_f32_e32 v239, v239, v95
	v_add_f32_e32 v242, v242, v96
	v_add_f32_e32 v243, v243, v97
	s_waitcnt lgkmcnt(0)
	s_barrier
	ds_read_b128 v[206:209], v162 offset:13440
	ds_read_b128 v[210:213], v162 offset:20096
	ds_read_b128 v[214:217], v162 offset:13472
	ds_read_b128 v[248:251], v162 offset:20128
	v_mfma_f32_32x32x16_bf16 v[14:29], v[134:137], v[152:155], v[14:29]
	ds_read_b128 v[134:137], v162 offset:13312
	v_cvt_pk_bf16_f32 v222, v86, v87
	v_cvt_pk_bf16_f32 v223, v88, v89
	v_cvt_pk_bf16_f32 v224, v90, v91
	v_cvt_pk_bf16_f32 v225, v92, v93
	v_cvt_pk_bf16_f32 v230, v94, v95
	v_cvt_pk_bf16_f32 v231, v96, v97
	v_mfma_f32_32x32x16_bf16 v[30:45], v[138:141], v[152:155], v[30:45]
	ds_read_b128 v[138:141], v162 offset:19968
	v_cvt_pk_bf16_f32 v232, v98, v99
	v_cvt_pk_bf16_f32 v233, v100, v101
	v_add_f32_e32 v238, v238, v98
	v_add_f32_e32 v239, v239, v99
	v_add_f32_e32 v242, v242, v100
	v_add_f32_e32 v243, v243, v101
	v_mfma_f32_32x32x16_bf16 v[14:29], v[142:145], v[222:225], v[14:29]
	ds_read_b128 v[142:145], v162 offset:13344
	v_cvt_pk_bf16_f32 v234, v102, v103
	v_cvt_pk_bf16_f32 v235, v104, v105
	v_cvt_pk_bf16_f32 v236, v106, v107
	v_cvt_pk_bf16_f32 v237, v108, v109
	v_add_f32_e32 v238, v238, v102
	v_add_f32_e32 v239, v239, v103
	v_mfma_f32_32x32x16_bf16 v[30:45], v[168:171], v[222:225], v[30:45]
	ds_read_b128 v[168:171], v162 offset:20000
	v_add_f32_e32 v242, v242, v104
	v_add_f32_e32 v243, v243, v105
	v_add_f32_e32 v238, v238, v106
	v_add_f32_e32 v239, v239, v107
	v_add_f32_e32 v242, v242, v108
	v_add_f32_e32 v243, v243, v109
	v_add_f32_e32 v238, v238, v239
	v_mfma_f32_32x32x16_bf16 v[14:29], v[172:175], v[230:233], v[14:29]
	ds_read_b128 v[172:175], v162 offset:13376
	v_add_f32_e32 v242, v242, v243
	v_add_f32_e32 v238, v238, v242
	v_add_f32_e32 v165, v165, v238
	v_max3_f32 v240, v46, v47, v48
	v_max3_f32 v241, v49, v50, v51
	v_max3_f32 v240, v240, v52, v53
	v_mfma_f32_32x32x16_bf16 v[30:45], v[178:181], v[230:233], v[30:45]
	ds_read_b128 v[178:181], v162 offset:20032
	global_load_dwordx4 v[130:133], v227, s[54:55]
	v_max3_f32 v241, v241, v54, v55
	v_max3_f32 v240, v240, v56, v57
	v_max3_f32 v241, v241, v58, v59
	v_max3_f32 v240, v240, v60, v61
	v_max3_f32 v241, v241, v62, v63
	v_max3_f32 v240, v240, v64, v65
	v_mfma_f32_32x32x16_bf16 v[14:29], v[182:185], v[234:237], v[14:29]
	ds_read_b128 v[182:185], v162 offset:13408
	v_max3_f32 v241, v241, v66, v67
	v_max3_f32 v240, v240, v68, v69
	v_max3_f32 v241, v241, v70, v71
	v_max3_f32 v240, v240, v72, v73
	v_max3_f32 v241, v241, v74, v75
	v_mfma_f32_32x32x16_bf16 v[30:45], v[186:189], v[234:237], v[30:45]
	ds_read_b128 v[186:189], v162 offset:20064
	v_max3_f32 v240, v240, v76, v77
	v_max_f32_e32 v240, v240, v241
	v_mov_b32_e32 v241, v240
	s_nop 1
	v_permlane32_swap_b32_e32 v240, v241
	v_max_f32_e32 v244, v240, v241
	s_add_u32 s54, s54, 0x10000
	s_addc_u32 s55, s55, 0
	s_add_u32 s56, s56, 0x1000
	s_addc_u32 s57, s57, 0
.Lm3_tail2:
	s_cmp_gt_u32 s11, 2
	s_cbranch_scc1 .Lm3_t2_full
	s_cmp_eq_u32 s11, 2
	s_cbranch_scc1 .Lm3_t2_last
	s_waitcnt lgkmcnt(0)
	s_waitcnt vmcnt(0)
	ds_write_b128 v159, v[130:133] offset:34816
	s_waitcnt lgkmcnt(0)
	s_barrier
	s_add_u32 s54, s54, 0x10000
	s_addc_u32 s55, s55, 0
	s_add_u32 s56, s56, 0x1000
	s_addc_u32 s57, s57, 0
	s_branch .Lm3_tail3

.Lm3_resc_rett2l:
	s_waitcnt lgkmcnt(0)
	ds_read_b64_tr_b16 v[134:135], v161 offset:26624
	ds_read_b64_tr_b16 v[136:137], v161 offset:27136
	ds_read_b64_tr_b16 v[138:139], v161 offset:30720
	ds_read_b64_tr_b16 v[140:141], v161 offset:31232
	ds_read_b64_tr_b16 v[142:143], v161 offset:27648
	ds_read_b64_tr_b16 v[144:145], v161 offset:28160
	ds_read_b64_tr_b16 v[168:169], v161 offset:31744
	ds_read_b64_tr_b16 v[170:171], v161 offset:32256
	ds_read_b64_tr_b16 v[172:173], v161 offset:28672
	ds_read_b64_tr_b16 v[174:175], v161 offset:29184
	ds_read_b64_tr_b16 v[178:179], v161 offset:32768
	ds_read_b64_tr_b16 v[180:181], v161 offset:33280
	ds_read_b64_tr_b16 v[182:183], v161 offset:29696
	ds_read_b64_tr_b16 v[184:185], v161 offset:30208
	v_exp_f32_e32 v46, v46
	v_exp_f32_e32 v47, v47
	v_exp_f32_e32 v48, v48
	v_exp_f32_e32 v49, v49
	v_exp_f32_e32 v50, v50
	v_exp_f32_e32 v51, v51
	v_exp_f32_e32 v52, v52
	v_exp_f32_e32 v53, v53
	v_cvt_pk_bf16_f32 v152, v46, v47
	v_cvt_pk_bf16_f32 v153, v48, v49
	v_cvt_pk_bf16_f32 v154, v50, v51
	v_cvt_pk_bf16_f32 v155, v52, v53
	v_exp_f32_e32 v54, v54
	v_exp_f32_e32 v55, v55
	v_exp_f32_e32 v56, v56
	v_exp_f32_e32 v57, v57
	v_exp_f32_e32 v58, v58
	v_exp_f32_e32 v59, v59
	v_exp_f32_e32 v60, v60
	v_exp_f32_e32 v61, v61
	v_add_f32_e32 v238, v46, v47
	v_add_f32_e32 v239, v48, v49
	v_add_f32_e32 v242, v50, v51
	v_add_f32_e32 v243, v52, v53
	v_exp_f32_e32 v62, v62
	v_exp_f32_e32 v63, v63
	v_exp_f32_e32 v64, v64
	v_exp_f32_e32 v65, v65
	v_exp_f32_e32 v66, v66
	v_exp_f32_e32 v67, v67
	v_exp_f32_e32 v68, v68
	v_exp_f32_e32 v69, v69
	v_add_f32_e32 v238, v238, v54
	v_add_f32_e32 v239, v239, v55
	v_add_f32_e32 v242, v242, v56
	v_add_f32_e32 v243, v243, v57
	v_add_f32_e32 v238, v238, v58
	v_add_f32_e32 v239, v239, v59
	v_add_f32_e32 v242, v242, v60
	v_add_f32_e32 v243, v243, v61
	v_exp_f32_e32 v70, v70
	v_exp_f32_e32 v71, v71
	v_exp_f32_e32 v72, v72
	v_exp_f32_e32 v73, v73
	v_exp_f32_e32 v74, v74
	v_exp_f32_e32 v75, v75
	v_exp_f32_e32 v76, v76
	v_exp_f32_e32 v77, v77
	v_add_f32_e32 v238, v238, v62
	v_add_f32_e32 v239, v239, v63
	v_add_f32_e32 v242, v242, v64
	v_add_f32_e32 v243, v243, v65
	s_waitcnt lgkmcnt(8)
	ds_read_b64_tr_b16 v[186:187], v161 offset:33792
	ds_read_b64_tr_b16 v[188:189], v161 offset:34304
	s_waitcnt vmcnt(0)
	ds_write_b128 v159, v[130:133] offset:34816
	s_waitcnt lgkmcnt(0)
	s_barrier
	v_mfma_f32_32x32x16_bf16 v[14:29], v[134:137], v[152:155], v[14:29]
	v_cvt_pk_bf16_f32 v222, v54, v55
	v_cvt_pk_bf16_f32 v223, v56, v57
	v_cvt_pk_bf16_f32 v224, v58, v59
	v_mfma_f32_32x32x16_bf16 v[30:45], v[138:141], v[152:155], v[30:45]
	v_cvt_pk_bf16_f32 v225, v60, v61
	v_cvt_pk_bf16_f32 v230, v62, v63
	v_cvt_pk_bf16_f32 v231, v64, v65
	v_mfma_f32_32x32x16_bf16 v[14:29], v[142:145], v[222:225], v[14:29]
	v_cvt_pk_bf16_f32 v232, v66, v67
	v_cvt_pk_bf16_f32 v233, v68, v69
	v_add_f32_e32 v238, v238, v66
	v_mfma_f32_32x32x16_bf16 v[30:45], v[168:171], v[222:225], v[30:45]
	v_add_f32_e32 v239, v239, v67
	v_add_f32_e32 v242, v242, v68
	v_add_f32_e32 v243, v243, v69
	v_cvt_pk_bf16_f32 v234, v70, v71
	v_mfma_f32_32x32x16_bf16 v[14:29], v[172:175], v[230:233], v[14:29]
	v_cvt_pk_bf16_f32 v235, v72, v73
	v_cvt_pk_bf16_f32 v236, v74, v75
	v_cvt_pk_bf16_f32 v237, v76, v77
	v_mfma_f32_32x32x16_bf16 v[30:45], v[178:181], v[230:233], v[30:45]
	v_add_f32_e32 v238, v238, v70
	v_add_f32_e32 v239, v239, v71
	v_add_f32_e32 v242, v242, v72
	v_add_f32_e32 v243, v243, v73
	v_mfma_f32_32x32x16_bf16 v[14:29], v[182:185], v[234:237], v[14:29]
	v_add_f32_e32 v238, v238, v74
	v_add_f32_e32 v239, v239, v75
	v_add_f32_e32 v242, v242, v76
	v_add_f32_e32 v243, v243, v77
	v_mfma_f32_32x32x16_bf16 v[30:45], v[186:189], v[234:237], v[30:45]
	v_add_f32_e32 v238, v238, v239
	v_add_f32_e32 v242, v242, v243
	v_add_f32_e32 v238, v238, v242
	v_add_f32_e32 v165, v165, v238
	s_add_u32 s54, s54, 0x10000
	s_addc_u32 s55, s55, 0
	s_add_u32 s56, s56, 0x1000
	s_addc_u32 s57, s57, 0
	s_branch .Lm3_tail3

.Lm3_resc_rett2f:
	s_waitcnt lgkmcnt(7)
	v_mfma_f32_32x32x16_bf16 v[78:93], v[134:137], v[0:3], v[190:205]
	ds_read_b64_tr_b16 v[134:135], v161 offset:26624
	ds_read_b64_tr_b16 v[136:137], v161 offset:27136
	v_exp_f32_e32 v46, v46
	v_exp_f32_e32 v47, v47
	v_exp_f32_e32 v48, v48
	v_exp_f32_e32 v49, v49
	s_waitcnt lgkmcnt(8)
	v_mfma_f32_32x32x16_bf16 v[94:109], v[138:141], v[0:3], v[190:205]
	ds_read_b64_tr_b16 v[138:139], v161 offset:30720
	ds_read_b64_tr_b16 v[140:141], v161 offset:31232
	v_exp_f32_e32 v50, v50
	v_exp_f32_e32 v51, v51
	v_exp_f32_e32 v52, v52
	v_exp_f32_e32 v53, v53
	s_waitcnt lgkmcnt(9)
	v_mfma_f32_32x32x16_bf16 v[78:93], v[142:145], v[4:7], v[78:93]
	ds_read_b64_tr_b16 v[142:143], v161 offset:27648
	ds_read_b64_tr_b16 v[144:145], v161 offset:28160
	v_cvt_pk_bf16_f32 v152, v46, v47
	v_cvt_pk_bf16_f32 v153, v48, v49
	v_cvt_pk_bf16_f32 v154, v50, v51
	v_cvt_pk_bf16_f32 v155, v52, v53
	s_waitcnt lgkmcnt(10)
	v_mfma_f32_32x32x16_bf16 v[94:109], v[168:171], v[4:7], v[94:109]
	ds_read_b64_tr_b16 v[168:169], v161 offset:31744
	ds_read_b64_tr_b16 v[170:171], v161 offset:32256
	v_exp_f32_e32 v54, v54
	v_exp_f32_e32 v55, v55
	v_exp_f32_e32 v56, v56
	v_exp_f32_e32 v57, v57
	s_waitcnt lgkmcnt(11)
	v_mfma_f32_32x32x16_bf16 v[78:93], v[172:175], v[8:11], v[78:93]
	ds_read_b64_tr_b16 v[172:173], v161 offset:28672
	ds_read_b64_tr_b16 v[174:175], v161 offset:29184
	v_exp_f32_e32 v58, v58
	v_exp_f32_e32 v59, v59
	v_exp_f32_e32 v60, v60
	s_waitcnt lgkmcnt(12)
	v_mfma_f32_32x32x16_bf16 v[94:109], v[178:181], v[8:11], v[94:109]
	ds_read_b64_tr_b16 v[178:179], v161 offset:32768
	ds_read_b64_tr_b16 v[180:181], v161 offset:33280
	v_exp_f32_e32 v61, v61
	v_add_f32_e32 v238, v46, v47
	v_add_f32_e32 v239, v48, v49
	v_add_f32_e32 v242, v50, v51
	v_add_f32_e32 v243, v52, v53
	v_exp_f32_e32 v62, v62
	s_waitcnt lgkmcnt(13)
	v_mfma_f32_32x32x16_bf16 v[78:93], v[182:185], v[110:113], v[78:93]
	ds_read_b64_tr_b16 v[182:183], v161 offset:29696
	ds_read_b64_tr_b16 v[184:185], v161 offset:30208
	v_exp_f32_e32 v63, v63
	v_exp_f32_e32 v64, v64
	v_exp_f32_e32 v65, v65
	v_exp_f32_e32 v66, v66
	s_waitcnt lgkmcnt(14)
	v_mfma_f32_32x32x16_bf16 v[94:109], v[186:189], v[110:113], v[94:109]
	s_waitcnt lgkmcnt(13)
	ds_read_b64_tr_b16 v[186:187], v161 offset:33792
	ds_read_b64_tr_b16 v[188:189], v161 offset:34304
	v_exp_f32_e32 v67, v67
	v_exp_f32_e32 v68, v68
	v_exp_f32_e32 v69, v69
	v_mfma_f32_32x32x16_bf16 v[78:93], v[206:209], v[114:117], v[78:93]
	v_add_f32_e32 v238, v238, v54
	v_add_f32_e32 v239, v239, v55
	v_add_f32_e32 v242, v242, v56
	v_add_f32_e32 v243, v243, v57
	v_add_f32_e32 v238, v238, v58
	v_add_f32_e32 v239, v239, v59
	v_add_f32_e32 v242, v242, v60
	s_waitcnt lgkmcnt(8)
	s_waitcnt vmcnt(0)
	ds_write_b128 v159, v[130:133] offset:34816
	v_mfma_f32_32x32x16_bf16 v[94:109], v[210:213], v[114:117], v[94:109]
	v_add_f32_e32 v243, v243, v61
	v_exp_f32_e32 v70, v70
	v_exp_f32_e32 v71, v71
	v_exp_f32_e32 v72, v72
	v_mfma_f32_32x32x16_bf16 v[78:93], v[214:217], v[118:121], v[78:93]
	v_exp_f32_e32 v73, v73
	v_exp_f32_e32 v74, v74
	v_exp_f32_e32 v75, v75
	v_exp_f32_e32 v76, v76
	v_mfma_f32_32x32x16_bf16 v[94:109], v[248:251], v[118:121], v[94:109]
	v_exp_f32_e32 v77, v77
	v_add_f32_e32 v238, v238, v62
	v_add_f32_e32 v239, v239, v63
	v_add_f32_e32 v242, v242, v64
	v_add_f32_e32 v243, v243, v65
	s_waitcnt lgkmcnt(0)
	s_barrier
	ds_read_b128 v[206:209], v162 offset:128
	ds_read_b128 v[210:213], v162 offset:6784
	ds_read_b128 v[214:217], v162 offset:160
	ds_read_b128 v[248:251], v162 offset:6816
	v_mfma_f32_32x32x16_bf16 v[14:29], v[134:137], v[152:155], v[14:29]
	ds_read_b128 v[134:137], v162
	v_cvt_pk_bf16_f32 v222, v54, v55
	v_cvt_pk_bf16_f32 v223, v56, v57
	v_cvt_pk_bf16_f32 v224, v58, v59
	v_cvt_pk_bf16_f32 v225, v60, v61
	v_cvt_pk_bf16_f32 v230, v62, v63
	v_cvt_pk_bf16_f32 v231, v64, v65
	v_mfma_f32_32x32x16_bf16 v[30:45], v[138:141], v[152:155], v[30:45]
	ds_read_b128 v[138:141], v162 offset:6656
	v_cvt_pk_bf16_f32 v232, v66, v67
	v_cvt_pk_bf16_f32 v233, v68, v69
	v_add_f32_e32 v238, v238, v66
	v_add_f32_e32 v239, v239, v67
	v_add_f32_e32 v242, v242, v68
	v_add_f32_e32 v243, v243, v69
	v_mfma_f32_32x32x16_bf16 v[14:29], v[142:145], v[222:225], v[14:29]
	ds_read_b128 v[142:145], v162 offset:32
	v_cvt_pk_bf16_f32 v234, v70, v71
	v_cvt_pk_bf16_f32 v235, v72, v73
	v_cvt_pk_bf16_f32 v236, v74, v75
	v_cvt_pk_bf16_f32 v237, v76, v77
	v_add_f32_e32 v238, v238, v70
	v_add_f32_e32 v239, v239, v71
	v_mfma_f32_32x32x16_bf16 v[30:45], v[168:171], v[222:225], v[30:45]
	ds_read_b128 v[168:171], v162 offset:6688
	v_add_f32_e32 v242, v242, v72
	v_add_f32_e32 v243, v243, v73
	v_add_f32_e32 v238, v238, v74
	v_add_f32_e32 v239, v239, v75
	v_add_f32_e32 v242, v242, v76
	v_add_f32_e32 v243, v243, v77
	v_add_f32_e32 v238, v238, v239
	v_mfma_f32_32x32x16_bf16 v[14:29], v[172:175], v[230:233], v[14:29]
	ds_read_b128 v[172:175], v162 offset:64
	v_add_f32_e32 v242, v242, v243
	v_add_f32_e32 v238, v238, v242
	v_add_f32_e32 v165, v165, v238
	v_max3_f32 v240, v78, v79, v80
	v_max3_f32 v241, v81, v82, v83
	v_max3_f32 v240, v240, v84, v85
	v_mfma_f32_32x32x16_bf16 v[30:45], v[178:181], v[230:233], v[30:45]
	ds_read_b128 v[178:181], v162 offset:6720
	v_max3_f32 v241, v241, v86, v87
	v_max3_f32 v240, v240, v88, v89
	v_max3_f32 v241, v241, v90, v91
	v_max3_f32 v240, v240, v92, v93
	v_max3_f32 v241, v241, v94, v95
	v_max3_f32 v240, v240, v96, v97
	v_mfma_f32_32x32x16_bf16 v[14:29], v[182:185], v[234:237], v[14:29]
	ds_read_b128 v[182:185], v162 offset:96
	v_max3_f32 v241, v241, v98, v99
	v_max3_f32 v240, v240, v100, v101
	v_max3_f32 v241, v241, v102, v103
	v_max3_f32 v240, v240, v104, v105
	v_max3_f32 v241, v241, v106, v107
	v_mfma_f32_32x32x16_bf16 v[30:45], v[186:189], v[234:237], v[30:45]
	ds_read_b128 v[186:189], v162 offset:6752
	v_max3_f32 v240, v240, v108, v109
	v_max_f32_e32 v240, v240, v241
	v_mov_b32_e32 v241, v240
	s_nop 1
	v_permlane32_swap_b32_e32 v240, v241
	v_max_f32_e32 v244, v240, v241
	s_add_u32 s54, s54, 0x10000
	s_addc_u32 s55, s55, 0
	s_add_u32 s56, s56, 0x1000
	s_addc_u32 s57, s57, 0
.Lm3_tail3:
	s_cmp_eq_u32 s11, 3
	s_cbranch_scc1 .Lm3_t3_last
	s_waitcnt lgkmcnt(0)
	s_waitcnt lgkmcnt(0)
	s_barrier
	s_add_u32 s54, s54, 0x10000
	s_addc_u32 s55, s55, 0
	s_add_u32 s56, s56, 0x1000
	s_addc_u32 s57, s57, 0
	s_branch .Lm3_done

.Lm3_resc_rett3l:
	s_waitcnt lgkmcnt(0)
	ds_read_b64_tr_b16 v[134:135], v161 offset:34816
	ds_read_b64_tr_b16 v[136:137], v161 offset:35328
	ds_read_b64_tr_b16 v[138:139], v161 offset:38912
	ds_read_b64_tr_b16 v[140:141], v161 offset:39424
	ds_read_b64_tr_b16 v[142:143], v161 offset:35840
	ds_read_b64_tr_b16 v[144:145], v161 offset:36352
	ds_read_b64_tr_b16 v[168:169], v161 offset:39936
	ds_read_b64_tr_b16 v[170:171], v161 offset:40448
	ds_read_b64_tr_b16 v[172:173], v161 offset:36864
	ds_read_b64_tr_b16 v[174:175], v161 offset:37376
	ds_read_b64_tr_b16 v[178:179], v161 offset:40960
	ds_read_b64_tr_b16 v[180:181], v161 offset:41472
	ds_read_b64_tr_b16 v[182:183], v161 offset:37888
	ds_read_b64_tr_b16 v[184:185], v161 offset:38400
	v_exp_f32_e32 v78, v78
	v_exp_f32_e32 v79, v79
	v_exp_f32_e32 v80, v80
	v_exp_f32_e32 v81, v81
	v_exp_f32_e32 v82, v82
	v_exp_f32_e32 v83, v83
	v_exp_f32_e32 v84, v84
	v_exp_f32_e32 v85, v85
	v_cvt_pk_bf16_f32 v152, v78, v79
	v_cvt_pk_bf16_f32 v153, v80, v81
	v_cvt_pk_bf16_f32 v154, v82, v83
	v_cvt_pk_bf16_f32 v155, v84, v85
	v_exp_f32_e32 v86, v86
	v_exp_f32_e32 v87, v87
	v_exp_f32_e32 v88, v88
	v_exp_f32_e32 v89, v89
	v_exp_f32_e32 v90, v90
	v_exp_f32_e32 v91, v91
	v_exp_f32_e32 v92, v92
	v_exp_f32_e32 v93, v93
	v_add_f32_e32 v238, v78, v79
	v_add_f32_e32 v239, v80, v81
	v_add_f32_e32 v242, v82, v83
	v_add_f32_e32 v243, v84, v85
	v_exp_f32_e32 v94, v94
	v_exp_f32_e32 v95, v95
	v_exp_f32_e32 v96, v96
	v_exp_f32_e32 v97, v97
	v_exp_f32_e32 v98, v98
	v_exp_f32_e32 v99, v99
	v_exp_f32_e32 v100, v100
	v_exp_f32_e32 v101, v101
	v_add_f32_e32 v238, v238, v86
	v_add_f32_e32 v239, v239, v87
	v_add_f32_e32 v242, v242, v88
	v_add_f32_e32 v243, v243, v89
	v_add_f32_e32 v238, v238, v90
	v_add_f32_e32 v239, v239, v91
	v_add_f32_e32 v242, v242, v92
	v_add_f32_e32 v243, v243, v93
	v_exp_f32_e32 v102, v102
	v_exp_f32_e32 v103, v103
	v_exp_f32_e32 v104, v104
	v_exp_f32_e32 v105, v105
	v_exp_f32_e32 v106, v106
	v_exp_f32_e32 v107, v107
	v_exp_f32_e32 v108, v108
	v_exp_f32_e32 v109, v109
	v_add_f32_e32 v238, v238, v94
	v_add_f32_e32 v239, v239, v95
	v_add_f32_e32 v242, v242, v96
	v_add_f32_e32 v243, v243, v97
	s_waitcnt lgkmcnt(8)
	ds_read_b64_tr_b16 v[186:187], v161 offset:41984
	ds_read_b64_tr_b16 v[188:189], v161 offset:42496
	s_waitcnt lgkmcnt(0)
	s_barrier
	v_mfma_f32_32x32x16_bf16 v[14:29], v[134:137], v[152:155], v[14:29]
	v_cvt_pk_bf16_f32 v222, v86, v87
	v_cvt_pk_bf16_f32 v223, v88, v89
	v_cvt_pk_bf16_f32 v224, v90, v91
	v_mfma_f32_32x32x16_bf16 v[30:45], v[138:141], v[152:155], v[30:45]
	v_cvt_pk_bf16_f32 v225, v92, v93
	v_cvt_pk_bf16_f32 v230, v94, v95
	v_cvt_pk_bf16_f32 v231, v96, v97
	v_mfma_f32_32x32x16_bf16 v[14:29], v[142:145], v[222:225], v[14:29]
	v_cvt_pk_bf16_f32 v232, v98, v99
	v_cvt_pk_bf16_f32 v233, v100, v101
	v_add_f32_e32 v238, v238, v98
	v_mfma_f32_32x32x16_bf16 v[30:45], v[168:171], v[222:225], v[30:45]
	v_add_f32_e32 v239, v239, v99
	v_add_f32_e32 v242, v242, v100
	v_add_f32_e32 v243, v243, v101
	v_cvt_pk_bf16_f32 v234, v102, v103
	v_mfma_f32_32x32x16_bf16 v[14:29], v[172:175], v[230:233], v[14:29]
	v_cvt_pk_bf16_f32 v235, v104, v105
	v_cvt_pk_bf16_f32 v236, v106, v107
	v_cvt_pk_bf16_f32 v237, v108, v109
	v_mfma_f32_32x32x16_bf16 v[30:45], v[178:181], v[230:233], v[30:45]
	v_add_f32_e32 v238, v238, v102
	v_add_f32_e32 v239, v239, v103
	v_add_f32_e32 v242, v242, v104
	v_add_f32_e32 v243, v243, v105
	v_mfma_f32_32x32x16_bf16 v[14:29], v[182:185], v[234:237], v[14:29]
	v_add_f32_e32 v238, v238, v106
	v_add_f32_e32 v239, v239, v107
	v_add_f32_e32 v242, v242, v108
	v_add_f32_e32 v243, v243, v109
	v_mfma_f32_32x32x16_bf16 v[30:45], v[186:189], v[234:237], v[30:45]
	v_add_f32_e32 v238, v238, v239
	v_add_f32_e32 v242, v242, v243
	v_add_f32_e32 v238, v238, v242
	v_add_f32_e32 v165, v165, v238
	s_add_u32 s54, s54, 0x10000
	s_addc_u32 s55, s55, 0
	s_add_u32 s56, s56, 0x1000
	s_addc_u32 s57, s57, 0
.Lm3_done:
	s_waitcnt vmcnt(0) lgkmcnt(0)
	s_branch .LBB0_629

.Lm3_rescb:
	s_nop 15
	v_max_f32_e32 v245, 0, v244
	v_sub_f32_e32 v246, 0, v245
	v_exp_f32_e32 v246, v246
	v_add_f32_e32 v164, v164, v245
	v_sub_f32_e32 v190, v190, v245
	v_sub_f32_e32 v191, v191, v245
	v_sub_f32_e32 v192, v192, v245
	v_sub_f32_e32 v193, v193, v245
	v_sub_f32_e32 v194, v194, v245
	v_sub_f32_e32 v195, v195, v245
	v_sub_f32_e32 v196, v196, v245
	v_sub_f32_e32 v197, v197, v245
	v_sub_f32_e32 v198, v198, v245
	v_sub_f32_e32 v199, v199, v245
	v_sub_f32_e32 v200, v200, v245
	v_sub_f32_e32 v201, v201, v245
	v_sub_f32_e32 v202, v202, v245
	v_sub_f32_e32 v203, v203, v245
	v_sub_f32_e32 v204, v204, v245
	v_sub_f32_e32 v205, v205, v245
	v_mul_f32_e32 v165, v165, v246
	v_mul_f32_e32 v14, v14, v246
	v_mul_f32_e32 v15, v15, v246
	v_mul_f32_e32 v16, v16, v246
	v_mul_f32_e32 v17, v17, v246
	v_mul_f32_e32 v18, v18, v246
	v_mul_f32_e32 v19, v19, v246
	v_mul_f32_e32 v20, v20, v246
	v_mul_f32_e32 v21, v21, v246
	v_mul_f32_e32 v22, v22, v246
	v_mul_f32_e32 v23, v23, v246
	v_mul_f32_e32 v24, v24, v246
	v_mul_f32_e32 v25, v25, v246
	v_mul_f32_e32 v26, v26, v246
	v_mul_f32_e32 v27, v27, v246
	v_mul_f32_e32 v28, v28, v246
	v_mul_f32_e32 v29, v29, v246
	v_mul_f32_e32 v30, v30, v246
	v_mul_f32_e32 v31, v31, v246
	v_mul_f32_e32 v32, v32, v246
	v_mul_f32_e32 v33, v33, v246
	v_mul_f32_e32 v34, v34, v246
	v_mul_f32_e32 v35, v35, v246
	v_mul_f32_e32 v36, v36, v246
	v_mul_f32_e32 v37, v37, v246
	v_mul_f32_e32 v38, v38, v246
	v_mul_f32_e32 v39, v39, v246
	v_mul_f32_e32 v40, v40, v246
	v_mul_f32_e32 v41, v41, v246
	v_mul_f32_e32 v42, v42, v246
	v_mul_f32_e32 v43, v43, v246
	v_mul_f32_e32 v44, v44, v246
	v_mul_f32_e32 v45, v45, v246
	v_sub_f32_e32 v78, v78, v245
	v_sub_f32_e32 v79, v79, v245
	v_sub_f32_e32 v80, v80, v245
	v_sub_f32_e32 v81, v81, v245
	v_sub_f32_e32 v82, v82, v245
	v_sub_f32_e32 v83, v83, v245
	v_sub_f32_e32 v84, v84, v245
	v_sub_f32_e32 v85, v85, v245
	v_sub_f32_e32 v86, v86, v245
	v_sub_f32_e32 v87, v87, v245
	v_sub_f32_e32 v88, v88, v245
	v_sub_f32_e32 v89, v89, v245
	v_sub_f32_e32 v90, v90, v245
	v_sub_f32_e32 v91, v91, v245
	v_sub_f32_e32 v92, v92, v245
	v_sub_f32_e32 v93, v93, v245
	v_sub_f32_e32 v94, v94, v245
	v_sub_f32_e32 v95, v95, v245
	v_sub_f32_e32 v96, v96, v245
	v_sub_f32_e32 v97, v97, v245
	v_sub_f32_e32 v98, v98, v245
	v_sub_f32_e32 v99, v99, v245
	v_sub_f32_e32 v100, v100, v245
	v_sub_f32_e32 v101, v101, v245
	v_sub_f32_e32 v102, v102, v245
	v_sub_f32_e32 v103, v103, v245
	v_sub_f32_e32 v104, v104, v245
	v_sub_f32_e32 v105, v105, v245
	v_sub_f32_e32 v106, v106, v245
	v_sub_f32_e32 v107, v107, v245
	v_sub_f32_e32 v108, v108, v245
	v_sub_f32_e32 v109, v109, v245
	s_branch .Lm3_resc_retb
.Lm3_resct0l:
	s_nop 15
	v_max_f32_e32 v245, 0, v244
	v_sub_f32_e32 v246, 0, v245
	v_exp_f32_e32 v246, v246
	v_add_f32_e32 v164, v164, v245
	v_sub_f32_e32 v190, v190, v245
	v_sub_f32_e32 v191, v191, v245
	v_sub_f32_e32 v192, v192, v245
	v_sub_f32_e32 v193, v193, v245
	v_sub_f32_e32 v194, v194, v245
	v_sub_f32_e32 v195, v195, v245
	v_sub_f32_e32 v196, v196, v245
	v_sub_f32_e32 v197, v197, v245
	v_sub_f32_e32 v198, v198, v245
	v_sub_f32_e32 v199, v199, v245
	v_sub_f32_e32 v200, v200, v245
	v_sub_f32_e32 v201, v201, v245
	v_sub_f32_e32 v202, v202, v245
	v_sub_f32_e32 v203, v203, v245
	v_sub_f32_e32 v204, v204, v245
	v_sub_f32_e32 v205, v205, v245
	v_mul_f32_e32 v165, v165, v246
	v_mul_f32_e32 v14, v14, v246
	v_mul_f32_e32 v15, v15, v246
	v_mul_f32_e32 v16, v16, v246
	v_mul_f32_e32 v17, v17, v246
	v_mul_f32_e32 v18, v18, v246
	v_mul_f32_e32 v19, v19, v246
	v_mul_f32_e32 v20, v20, v246
	v_mul_f32_e32 v21, v21, v246
	v_mul_f32_e32 v22, v22, v246
	v_mul_f32_e32 v23, v23, v246
	v_mul_f32_e32 v24, v24, v246
	v_mul_f32_e32 v25, v25, v246
	v_mul_f32_e32 v26, v26, v246
	v_mul_f32_e32 v27, v27, v246
	v_mul_f32_e32 v28, v28, v246
	v_mul_f32_e32 v29, v29, v246
	v_mul_f32_e32 v30, v30, v246
	v_mul_f32_e32 v31, v31, v246
	v_mul_f32_e32 v32, v32, v246
	v_mul_f32_e32 v33, v33, v246
	v_mul_f32_e32 v34, v34, v246
	v_mul_f32_e32 v35, v35, v246
	v_mul_f32_e32 v36, v36, v246
	v_mul_f32_e32 v37, v37, v246
	v_mul_f32_e32 v38, v38, v246
	v_mul_f32_e32 v39, v39, v246
	v_mul_f32_e32 v40, v40, v246
	v_mul_f32_e32 v41, v41, v246
	v_mul_f32_e32 v42, v42, v246
	v_mul_f32_e32 v43, v43, v246
	v_mul_f32_e32 v44, v44, v246
	v_mul_f32_e32 v45, v45, v246
	v_sub_f32_e32 v46, v46, v245
	v_sub_f32_e32 v47, v47, v245
	v_sub_f32_e32 v48, v48, v245
	v_sub_f32_e32 v49, v49, v245
	v_sub_f32_e32 v50, v50, v245
	v_sub_f32_e32 v51, v51, v245
	v_sub_f32_e32 v52, v52, v245
	v_sub_f32_e32 v53, v53, v245
	v_sub_f32_e32 v54, v54, v245
	v_sub_f32_e32 v55, v55, v245
	v_sub_f32_e32 v56, v56, v245
	v_sub_f32_e32 v57, v57, v245
	v_sub_f32_e32 v58, v58, v245
	v_sub_f32_e32 v59, v59, v245
	v_sub_f32_e32 v60, v60, v245
	v_sub_f32_e32 v61, v61, v245
	v_sub_f32_e32 v62, v62, v245
	v_sub_f32_e32 v63, v63, v245
	v_sub_f32_e32 v64, v64, v245
	v_sub_f32_e32 v65, v65, v245
	v_sub_f32_e32 v66, v66, v245
	v_sub_f32_e32 v67, v67, v245
	v_sub_f32_e32 v68, v68, v245
	v_sub_f32_e32 v69, v69, v245
	v_sub_f32_e32 v70, v70, v245
	v_sub_f32_e32 v71, v71, v245
	v_sub_f32_e32 v72, v72, v245
	v_sub_f32_e32 v73, v73, v245
	v_sub_f32_e32 v74, v74, v245
	v_sub_f32_e32 v75, v75, v245
	v_sub_f32_e32 v76, v76, v245
	v_sub_f32_e32 v77, v77, v245
	s_branch .Lm3_resc_rett0l
.Lm3_resct0f:
	s_nop 15
	v_max_f32_e32 v245, 0, v244
	v_sub_f32_e32 v246, 0, v245
	v_exp_f32_e32 v246, v246
	v_add_f32_e32 v164, v164, v245
	v_sub_f32_e32 v190, v190, v245
	v_sub_f32_e32 v191, v191, v245
	v_sub_f32_e32 v192, v192, v245
	v_sub_f32_e32 v193, v193, v245
	v_sub_f32_e32 v194, v194, v245
	v_sub_f32_e32 v195, v195, v245
	v_sub_f32_e32 v196, v196, v245
	v_sub_f32_e32 v197, v197, v245
	v_sub_f32_e32 v198, v198, v245
	v_sub_f32_e32 v199, v199, v245
	v_sub_f32_e32 v200, v200, v245
	v_sub_f32_e32 v201, v201, v245
	v_sub_f32_e32 v202, v202, v245
	v_sub_f32_e32 v203, v203, v245
	v_sub_f32_e32 v204, v204, v245
	v_sub_f32_e32 v205, v205, v245
	v_mul_f32_e32 v165, v165, v246
	v_mul_f32_e32 v14, v14, v246
	v_mul_f32_e32 v15, v15, v246
	v_mul_f32_e32 v16, v16, v246
	v_mul_f32_e32 v17, v17, v246
	v_mul_f32_e32 v18, v18, v246
	v_mul_f32_e32 v19, v19, v246
	v_mul_f32_e32 v20, v20, v246
	v_mul_f32_e32 v21, v21, v246
	v_mul_f32_e32 v22, v22, v246
	v_mul_f32_e32 v23, v23, v246
	v_mul_f32_e32 v24, v24, v246
	v_mul_f32_e32 v25, v25, v246
	v_mul_f32_e32 v26, v26, v246
	v_mul_f32_e32 v27, v27, v246
	v_mul_f32_e32 v28, v28, v246
	v_mul_f32_e32 v29, v29, v246
	v_mul_f32_e32 v30, v30, v246
	v_mul_f32_e32 v31, v31, v246
	v_mul_f32_e32 v32, v32, v246
	v_mul_f32_e32 v33, v33, v246
	v_mul_f32_e32 v34, v34, v246
	v_mul_f32_e32 v35, v35, v246
	v_mul_f32_e32 v36, v36, v246
	v_mul_f32_e32 v37, v37, v246
	v_mul_f32_e32 v38, v38, v246
	v_mul_f32_e32 v39, v39, v246
	v_mul_f32_e32 v40, v40, v246
	v_mul_f32_e32 v41, v41, v246
	v_mul_f32_e32 v42, v42, v246
	v_mul_f32_e32 v43, v43, v246
	v_mul_f32_e32 v44, v44, v246
	v_mul_f32_e32 v45, v45, v246
	v_sub_f32_e32 v46, v46, v245
	v_sub_f32_e32 v47, v47, v245
	v_sub_f32_e32 v48, v48, v245
	v_sub_f32_e32 v49, v49, v245
	v_sub_f32_e32 v50, v50, v245
	v_sub_f32_e32 v51, v51, v245
	v_sub_f32_e32 v52, v52, v245
	v_sub_f32_e32 v53, v53, v245
	v_sub_f32_e32 v54, v54, v245
	v_sub_f32_e32 v55, v55, v245
	v_sub_f32_e32 v56, v56, v245
	v_sub_f32_e32 v57, v57, v245
	v_sub_f32_e32 v58, v58, v245
	v_sub_f32_e32 v59, v59, v245
	v_sub_f32_e32 v60, v60, v245
	v_sub_f32_e32 v61, v61, v245
	v_sub_f32_e32 v62, v62, v245
	v_sub_f32_e32 v63, v63, v245
	v_sub_f32_e32 v64, v64, v245
	v_sub_f32_e32 v65, v65, v245
	v_sub_f32_e32 v66, v66, v245
	v_sub_f32_e32 v67, v67, v245
	v_sub_f32_e32 v68, v68, v245
	v_sub_f32_e32 v69, v69, v245
	v_sub_f32_e32 v70, v70, v245
	v_sub_f32_e32 v71, v71, v245
	v_sub_f32_e32 v72, v72, v245
	v_sub_f32_e32 v73, v73, v245
	v_sub_f32_e32 v74, v74, v245
	v_sub_f32_e32 v75, v75, v245
	v_sub_f32_e32 v76, v76, v245
	v_sub_f32_e32 v77, v77, v245
	s_branch .Lm3_resc_rett0f
.Lm3_resct1l:
	s_nop 15
	v_max_f32_e32 v245, 0, v244
	v_sub_f32_e32 v246, 0, v245
	v_exp_f32_e32 v246, v246
	v_add_f32_e32 v164, v164, v245
	v_sub_f32_e32 v190, v190, v245
	v_sub_f32_e32 v191, v191, v245
	v_sub_f32_e32 v192, v192, v245
	v_sub_f32_e32 v193, v193, v245
	v_sub_f32_e32 v194, v194, v245
	v_sub_f32_e32 v195, v195, v245
	v_sub_f32_e32 v196, v196, v245
	v_sub_f32_e32 v197, v197, v245
	v_sub_f32_e32 v198, v198, v245
	v_sub_f32_e32 v199, v199, v245
	v_sub_f32_e32 v200, v200, v245
	v_sub_f32_e32 v201, v201, v245
	v_sub_f32_e32 v202, v202, v245
	v_sub_f32_e32 v203, v203, v245
	v_sub_f32_e32 v204, v204, v245
	v_sub_f32_e32 v205, v205, v245
	v_mul_f32_e32 v165, v165, v246
	v_mul_f32_e32 v14, v14, v246
	v_mul_f32_e32 v15, v15, v246
	v_mul_f32_e32 v16, v16, v246
	v_mul_f32_e32 v17, v17, v246
	v_mul_f32_e32 v18, v18, v246
	v_mul_f32_e32 v19, v19, v246
	v_mul_f32_e32 v20, v20, v246
	v_mul_f32_e32 v21, v21, v246
	v_mul_f32_e32 v22, v22, v246
	v_mul_f32_e32 v23, v23, v246
	v_mul_f32_e32 v24, v24, v246
	v_mul_f32_e32 v25, v25, v246
	v_mul_f32_e32 v26, v26, v246
	v_mul_f32_e32 v27, v27, v246
	v_mul_f32_e32 v28, v28, v246
	v_mul_f32_e32 v29, v29, v246
	v_mul_f32_e32 v30, v30, v246
	v_mul_f32_e32 v31, v31, v246
	v_mul_f32_e32 v32, v32, v246
	v_mul_f32_e32 v33, v33, v246
	v_mul_f32_e32 v34, v34, v246
	v_mul_f32_e32 v35, v35, v246
	v_mul_f32_e32 v36, v36, v246
	v_mul_f32_e32 v37, v37, v246
	v_mul_f32_e32 v38, v38, v246
	v_mul_f32_e32 v39, v39, v246
	v_mul_f32_e32 v40, v40, v246
	v_mul_f32_e32 v41, v41, v246
	v_mul_f32_e32 v42, v42, v246
	v_mul_f32_e32 v43, v43, v246
	v_mul_f32_e32 v44, v44, v246
	v_mul_f32_e32 v45, v45, v246
	v_sub_f32_e32 v78, v78, v245
	v_sub_f32_e32 v79, v79, v245
	v_sub_f32_e32 v80, v80, v245
	v_sub_f32_e32 v81, v81, v245
	v_sub_f32_e32 v82, v82, v245
	v_sub_f32_e32 v83, v83, v245
	v_sub_f32_e32 v84, v84, v245
	v_sub_f32_e32 v85, v85, v245
	v_sub_f32_e32 v86, v86, v245
	v_sub_f32_e32 v87, v87, v245
	v_sub_f32_e32 v88, v88, v245
	v_sub_f32_e32 v89, v89, v245
	v_sub_f32_e32 v90, v90, v245
	v_sub_f32_e32 v91, v91, v245
	v_sub_f32_e32 v92, v92, v245
	v_sub_f32_e32 v93, v93, v245
	v_sub_f32_e32 v94, v94, v245
	v_sub_f32_e32 v95, v95, v245
	v_sub_f32_e32 v96, v96, v245
	v_sub_f32_e32 v97, v97, v245
	v_sub_f32_e32 v98, v98, v245
	v_sub_f32_e32 v99, v99, v245
	v_sub_f32_e32 v100, v100, v245
	v_sub_f32_e32 v101, v101, v245
	v_sub_f32_e32 v102, v102, v245
	v_sub_f32_e32 v103, v103, v245
	v_sub_f32_e32 v104, v104, v245
	v_sub_f32_e32 v105, v105, v245
	v_sub_f32_e32 v106, v106, v245
	v_sub_f32_e32 v107, v107, v245
	v_sub_f32_e32 v108, v108, v245
	v_sub_f32_e32 v109, v109, v245
	s_branch .Lm3_resc_rett1l
.Lm3_resct1f:
	s_nop 15
	v_max_f32_e32 v245, 0, v244
	v_sub_f32_e32 v246, 0, v245
	v_exp_f32_e32 v246, v246
	v_add_f32_e32 v164, v164, v245
	v_sub_f32_e32 v190, v190, v245
	v_sub_f32_e32 v191, v191, v245
	v_sub_f32_e32 v192, v192, v245
	v_sub_f32_e32 v193, v193, v245
	v_sub_f32_e32 v194, v194, v245
	v_sub_f32_e32 v195, v195, v245
	v_sub_f32_e32 v196, v196, v245
	v_sub_f32_e32 v197, v197, v245
	v_sub_f32_e32 v198, v198, v245
	v_sub_f32_e32 v199, v199, v245
	v_sub_f32_e32 v200, v200, v245
	v_sub_f32_e32 v201, v201, v245
	v_sub_f32_e32 v202, v202, v245
	v_sub_f32_e32 v203, v203, v245
	v_sub_f32_e32 v204, v204, v245
	v_sub_f32_e32 v205, v205, v245
	v_mul_f32_e32 v165, v165, v246
	v_mul_f32_e32 v14, v14, v246
	v_mul_f32_e32 v15, v15, v246
	v_mul_f32_e32 v16, v16, v246
	v_mul_f32_e32 v17, v17, v246
	v_mul_f32_e32 v18, v18, v246
	v_mul_f32_e32 v19, v19, v246
	v_mul_f32_e32 v20, v20, v246
	v_mul_f32_e32 v21, v21, v246
	v_mul_f32_e32 v22, v22, v246
	v_mul_f32_e32 v23, v23, v246
	v_mul_f32_e32 v24, v24, v246
	v_mul_f32_e32 v25, v25, v246
	v_mul_f32_e32 v26, v26, v246
	v_mul_f32_e32 v27, v27, v246
	v_mul_f32_e32 v28, v28, v246
	v_mul_f32_e32 v29, v29, v246
	v_mul_f32_e32 v30, v30, v246
	v_mul_f32_e32 v31, v31, v246
	v_mul_f32_e32 v32, v32, v246
	v_mul_f32_e32 v33, v33, v246
	v_mul_f32_e32 v34, v34, v246
	v_mul_f32_e32 v35, v35, v246
	v_mul_f32_e32 v36, v36, v246
	v_mul_f32_e32 v37, v37, v246
	v_mul_f32_e32 v38, v38, v246
	v_mul_f32_e32 v39, v39, v246
	v_mul_f32_e32 v40, v40, v246
	v_mul_f32_e32 v41, v41, v246
	v_mul_f32_e32 v42, v42, v246
	v_mul_f32_e32 v43, v43, v246
	v_mul_f32_e32 v44, v44, v246
	v_mul_f32_e32 v45, v45, v246
	v_sub_f32_e32 v78, v78, v245
	v_sub_f32_e32 v79, v79, v245
	v_sub_f32_e32 v80, v80, v245
	v_sub_f32_e32 v81, v81, v245
	v_sub_f32_e32 v82, v82, v245
	v_sub_f32_e32 v83, v83, v245
	v_sub_f32_e32 v84, v84, v245
	v_sub_f32_e32 v85, v85, v245
	v_sub_f32_e32 v86, v86, v245
	v_sub_f32_e32 v87, v87, v245
	v_sub_f32_e32 v88, v88, v245
	v_sub_f32_e32 v89, v89, v245
	v_sub_f32_e32 v90, v90, v245
	v_sub_f32_e32 v91, v91, v245
	v_sub_f32_e32 v92, v92, v245
	v_sub_f32_e32 v93, v93, v245
	v_sub_f32_e32 v94, v94, v245
	v_sub_f32_e32 v95, v95, v245
	v_sub_f32_e32 v96, v96, v245
	v_sub_f32_e32 v97, v97, v245
	v_sub_f32_e32 v98, v98, v245
	v_sub_f32_e32 v99, v99, v245
	v_sub_f32_e32 v100, v100, v245
	v_sub_f32_e32 v101, v101, v245
	v_sub_f32_e32 v102, v102, v245
	v_sub_f32_e32 v103, v103, v245
	v_sub_f32_e32 v104, v104, v245
	v_sub_f32_e32 v105, v105, v245
	v_sub_f32_e32 v106, v106, v245
	v_sub_f32_e32 v107, v107, v245
	v_sub_f32_e32 v108, v108, v245
	v_sub_f32_e32 v109, v109, v245
	s_branch .Lm3_resc_rett1f
.Lm3_resct2l:
	s_nop 15
	v_max_f32_e32 v245, 0, v244
	v_sub_f32_e32 v246, 0, v245
	v_exp_f32_e32 v246, v246
	v_add_f32_e32 v164, v164, v245
	v_sub_f32_e32 v190, v190, v245
	v_sub_f32_e32 v191, v191, v245
	v_sub_f32_e32 v192, v192, v245
	v_sub_f32_e32 v193, v193, v245
	v_sub_f32_e32 v194, v194, v245
	v_sub_f32_e32 v195, v195, v245
	v_sub_f32_e32 v196, v196, v245
	v_sub_f32_e32 v197, v197, v245
	v_sub_f32_e32 v198, v198, v245
	v_sub_f32_e32 v199, v199, v245
	v_sub_f32_e32 v200, v200, v245
	v_sub_f32_e32 v201, v201, v245
	v_sub_f32_e32 v202, v202, v245
	v_sub_f32_e32 v203, v203, v245
	v_sub_f32_e32 v204, v204, v245
	v_sub_f32_e32 v205, v205, v245
	v_mul_f32_e32 v165, v165, v246
	v_mul_f32_e32 v14, v14, v246
	v_mul_f32_e32 v15, v15, v246
	v_mul_f32_e32 v16, v16, v246
	v_mul_f32_e32 v17, v17, v246
	v_mul_f32_e32 v18, v18, v246
	v_mul_f32_e32 v19, v19, v246
	v_mul_f32_e32 v20, v20, v246
	v_mul_f32_e32 v21, v21, v246
	v_mul_f32_e32 v22, v22, v246
	v_mul_f32_e32 v23, v23, v246
	v_mul_f32_e32 v24, v24, v246
	v_mul_f32_e32 v25, v25, v246
	v_mul_f32_e32 v26, v26, v246
	v_mul_f32_e32 v27, v27, v246
	v_mul_f32_e32 v28, v28, v246
	v_mul_f32_e32 v29, v29, v246
	v_mul_f32_e32 v30, v30, v246
	v_mul_f32_e32 v31, v31, v246
	v_mul_f32_e32 v32, v32, v246
	v_mul_f32_e32 v33, v33, v246
	v_mul_f32_e32 v34, v34, v246
	v_mul_f32_e32 v35, v35, v246
	v_mul_f32_e32 v36, v36, v246
	v_mul_f32_e32 v37, v37, v246
	v_mul_f32_e32 v38, v38, v246
	v_mul_f32_e32 v39, v39, v246
	v_mul_f32_e32 v40, v40, v246
	v_mul_f32_e32 v41, v41, v246
	v_mul_f32_e32 v42, v42, v246
	v_mul_f32_e32 v43, v43, v246
	v_mul_f32_e32 v44, v44, v246
	v_mul_f32_e32 v45, v45, v246
	v_sub_f32_e32 v46, v46, v245
	v_sub_f32_e32 v47, v47, v245
	v_sub_f32_e32 v48, v48, v245
	v_sub_f32_e32 v49, v49, v245
	v_sub_f32_e32 v50, v50, v245
	v_sub_f32_e32 v51, v51, v245
	v_sub_f32_e32 v52, v52, v245
	v_sub_f32_e32 v53, v53, v245
	v_sub_f32_e32 v54, v54, v245
	v_sub_f32_e32 v55, v55, v245
	v_sub_f32_e32 v56, v56, v245
	v_sub_f32_e32 v57, v57, v245
	v_sub_f32_e32 v58, v58, v245
	v_sub_f32_e32 v59, v59, v245
	v_sub_f32_e32 v60, v60, v245
	v_sub_f32_e32 v61, v61, v245
	v_sub_f32_e32 v62, v62, v245
	v_sub_f32_e32 v63, v63, v245
	v_sub_f32_e32 v64, v64, v245
	v_sub_f32_e32 v65, v65, v245
	v_sub_f32_e32 v66, v66, v245
	v_sub_f32_e32 v67, v67, v245
	v_sub_f32_e32 v68, v68, v245
	v_sub_f32_e32 v69, v69, v245
	v_sub_f32_e32 v70, v70, v245
	v_sub_f32_e32 v71, v71, v245
	v_sub_f32_e32 v72, v72, v245
	v_sub_f32_e32 v73, v73, v245
	v_sub_f32_e32 v74, v74, v245
	v_sub_f32_e32 v75, v75, v245
	v_sub_f32_e32 v76, v76, v245
	v_sub_f32_e32 v77, v77, v245
	s_branch .Lm3_resc_rett2l
.Lm3_resct2f:
	s_nop 15
	v_max_f32_e32 v245, 0, v244
	v_sub_f32_e32 v246, 0, v245
	v_exp_f32_e32 v246, v246
	v_add_f32_e32 v164, v164, v245
	v_sub_f32_e32 v190, v190, v245
	v_sub_f32_e32 v191, v191, v245
	v_sub_f32_e32 v192, v192, v245
	v_sub_f32_e32 v193, v193, v245
	v_sub_f32_e32 v194, v194, v245
	v_sub_f32_e32 v195, v195, v245
	v_sub_f32_e32 v196, v196, v245
	v_sub_f32_e32 v197, v197, v245
	v_sub_f32_e32 v198, v198, v245
	v_sub_f32_e32 v199, v199, v245
	v_sub_f32_e32 v200, v200, v245
	v_sub_f32_e32 v201, v201, v245
	v_sub_f32_e32 v202, v202, v245
	v_sub_f32_e32 v203, v203, v245
	v_sub_f32_e32 v204, v204, v245
	v_sub_f32_e32 v205, v205, v245
	v_mul_f32_e32 v165, v165, v246
	v_mul_f32_e32 v14, v14, v246
	v_mul_f32_e32 v15, v15, v246
	v_mul_f32_e32 v16, v16, v246
	v_mul_f32_e32 v17, v17, v246
	v_mul_f32_e32 v18, v18, v246
	v_mul_f32_e32 v19, v19, v246
	v_mul_f32_e32 v20, v20, v246
	v_mul_f32_e32 v21, v21, v246
	v_mul_f32_e32 v22, v22, v246
	v_mul_f32_e32 v23, v23, v246
	v_mul_f32_e32 v24, v24, v246
	v_mul_f32_e32 v25, v25, v246
	v_mul_f32_e32 v26, v26, v246
	v_mul_f32_e32 v27, v27, v246
	v_mul_f32_e32 v28, v28, v246
	v_mul_f32_e32 v29, v29, v246
	v_mul_f32_e32 v30, v30, v246
	v_mul_f32_e32 v31, v31, v246
	v_mul_f32_e32 v32, v32, v246
	v_mul_f32_e32 v33, v33, v246
	v_mul_f32_e32 v34, v34, v246
	v_mul_f32_e32 v35, v35, v246
	v_mul_f32_e32 v36, v36, v246
	v_mul_f32_e32 v37, v37, v246
	v_mul_f32_e32 v38, v38, v246
	v_mul_f32_e32 v39, v39, v246
	v_mul_f32_e32 v40, v40, v246
	v_mul_f32_e32 v41, v41, v246
	v_mul_f32_e32 v42, v42, v246
	v_mul_f32_e32 v43, v43, v246
	v_mul_f32_e32 v44, v44, v246
	v_mul_f32_e32 v45, v45, v246
	v_sub_f32_e32 v46, v46, v245
	v_sub_f32_e32 v47, v47, v245
	v_sub_f32_e32 v48, v48, v245
	v_sub_f32_e32 v49, v49, v245
	v_sub_f32_e32 v50, v50, v245
	v_sub_f32_e32 v51, v51, v245
	v_sub_f32_e32 v52, v52, v245
	v_sub_f32_e32 v53, v53, v245
	v_sub_f32_e32 v54, v54, v245
	v_sub_f32_e32 v55, v55, v245
	v_sub_f32_e32 v56, v56, v245
	v_sub_f32_e32 v57, v57, v245
	v_sub_f32_e32 v58, v58, v245
	v_sub_f32_e32 v59, v59, v245
	v_sub_f32_e32 v60, v60, v245
	v_sub_f32_e32 v61, v61, v245
	v_sub_f32_e32 v62, v62, v245
	v_sub_f32_e32 v63, v63, v245
	v_sub_f32_e32 v64, v64, v245
	v_sub_f32_e32 v65, v65, v245
	v_sub_f32_e32 v66, v66, v245
	v_sub_f32_e32 v67, v67, v245
	v_sub_f32_e32 v68, v68, v245
	v_sub_f32_e32 v69, v69, v245
	v_sub_f32_e32 v70, v70, v245
	v_sub_f32_e32 v71, v71, v245
	v_sub_f32_e32 v72, v72, v245
	v_sub_f32_e32 v73, v73, v245
	v_sub_f32_e32 v74, v74, v245
	v_sub_f32_e32 v75, v75, v245
	v_sub_f32_e32 v76, v76, v245
	v_sub_f32_e32 v77, v77, v245
	s_branch .Lm3_resc_rett2f
.Lm3_resct3l:
	s_nop 15
	v_max_f32_e32 v245, 0, v244
	v_sub_f32_e32 v246, 0, v245
	v_exp_f32_e32 v246, v246
	v_add_f32_e32 v164, v164, v245
	v_sub_f32_e32 v190, v190, v245
	v_sub_f32_e32 v191, v191, v245
	v_sub_f32_e32 v192, v192, v245
	v_sub_f32_e32 v193, v193, v245
	v_sub_f32_e32 v194, v194, v245
	v_sub_f32_e32 v195, v195, v245
	v_sub_f32_e32 v196, v196, v245
	v_sub_f32_e32 v197, v197, v245
	v_sub_f32_e32 v198, v198, v245
	v_sub_f32_e32 v199, v199, v245
	v_sub_f32_e32 v200, v200, v245
	v_sub_f32_e32 v201, v201, v245
	v_sub_f32_e32 v202, v202, v245
	v_sub_f32_e32 v203, v203, v245
	v_sub_f32_e32 v204, v204, v245
	v_sub_f32_e32 v205, v205, v245
	v_mul_f32_e32 v165, v165, v246
	v_mul_f32_e32 v14, v14, v246
	v_mul_f32_e32 v15, v15, v246
	v_mul_f32_e32 v16, v16, v246
	v_mul_f32_e32 v17, v17, v246
	v_mul_f32_e32 v18, v18, v246
	v_mul_f32_e32 v19, v19, v246
	v_mul_f32_e32 v20, v20, v246
	v_mul_f32_e32 v21, v21, v246
	v_mul_f32_e32 v22, v22, v246
	v_mul_f32_e32 v23, v23, v246
	v_mul_f32_e32 v24, v24, v246
	v_mul_f32_e32 v25, v25, v246
	v_mul_f32_e32 v26, v26, v246
	v_mul_f32_e32 v27, v27, v246
	v_mul_f32_e32 v28, v28, v246
	v_mul_f32_e32 v29, v29, v246
	v_mul_f32_e32 v30, v30, v246
	v_mul_f32_e32 v31, v31, v246
	v_mul_f32_e32 v32, v32, v246
	v_mul_f32_e32 v33, v33, v246
	v_mul_f32_e32 v34, v34, v246
	v_mul_f32_e32 v35, v35, v246
	v_mul_f32_e32 v36, v36, v246
	v_mul_f32_e32 v37, v37, v246
	v_mul_f32_e32 v38, v38, v246
	v_mul_f32_e32 v39, v39, v246
	v_mul_f32_e32 v40, v40, v246
	v_mul_f32_e32 v41, v41, v246
	v_mul_f32_e32 v42, v42, v246
	v_mul_f32_e32 v43, v43, v246
	v_mul_f32_e32 v44, v44, v246
	v_mul_f32_e32 v45, v45, v246
	v_sub_f32_e32 v78, v78, v245
	v_sub_f32_e32 v79, v79, v245
	v_sub_f32_e32 v80, v80, v245
	v_sub_f32_e32 v81, v81, v245
	v_sub_f32_e32 v82, v82, v245
	v_sub_f32_e32 v83, v83, v245
	v_sub_f32_e32 v84, v84, v245
	v_sub_f32_e32 v85, v85, v245
	v_sub_f32_e32 v86, v86, v245
	v_sub_f32_e32 v87, v87, v245
	v_sub_f32_e32 v88, v88, v245
	v_sub_f32_e32 v89, v89, v245
	v_sub_f32_e32 v90, v90, v245
	v_sub_f32_e32 v91, v91, v245
	v_sub_f32_e32 v92, v92, v245
	v_sub_f32_e32 v93, v93, v245
	v_sub_f32_e32 v94, v94, v245
	v_sub_f32_e32 v95, v95, v245
	v_sub_f32_e32 v96, v96, v245
	v_sub_f32_e32 v97, v97, v245
	v_sub_f32_e32 v98, v98, v245
	v_sub_f32_e32 v99, v99, v245
	v_sub_f32_e32 v100, v100, v245
	v_sub_f32_e32 v101, v101, v245
	v_sub_f32_e32 v102, v102, v245
	v_sub_f32_e32 v103, v103, v245
	v_sub_f32_e32 v104, v104, v245
	v_sub_f32_e32 v105, v105, v245
	v_sub_f32_e32 v106, v106, v245
	v_sub_f32_e32 v107, v107, v245
	v_sub_f32_e32 v108, v108, v245
	v_sub_f32_e32 v109, v109, v245
	s_branch .Lm3_resc_rett3l
.LBB0_777:
	s_mov_b32 s3, s33
	v_mbcnt_lo_u32_b32 v0, -1, 0
	v_mbcnt_hi_u32_b32 v0, -1, v0
	s_waitcnt vmcnt(0)
	s_nop 0
	v_lshl_or_b32 v0, s3, 6, v0
	v_cmp_eq_u32_e32 vcc, 0, v0
	s_barrier
	s_and_saveexec_b64 s[4:5], vcc
	s_cbranch_execz .LBB0_829
	v_readlane_b32 s6, v254, 51
	s_getreg_b32 s3, hwreg(HW_REG_XCC_ID, 0, 4)
	s_waitcnt vmcnt(0) expcnt(0) lgkmcnt(0)
	v_mov_b32_e32 v0, s6
	ds_read_b32 v2, v0
	v_readlane_b32 s6, v254, 52
	s_and_b32 s3, s3, 15
	s_waitcnt lgkmcnt(0)
	v_cmp_ne_u32_e32 vcc, 0, v2
	v_mov_b32_e32 v0, s6
	ds_read_b32 v0, v0
	s_cbranch_vccnz .LBB0_793
	s_mov_b32 s12, 1
	s_branch .LBB0_781
